# pads between consecutive LDS-DMA issue blocks widened to s_nop 7, no setprio
# baseline (speedup 1.0000x reference)
.Lnb_p1:
	s_add_i32 s7, s4, 0xfff84000
	s_cmp_eq_u32 s6, 28
	s_cselect_b32 s17, s0, s7
	s_cselect_b32 s16, s1, s5
	s_or_b32 s7, s17, 0x4000
	s_mov_b32 m0, s79
	s_nop 0
	buffer_load_dwordx4 v242, s[24:27], s4 offen lds
	s_nop 7
	s_mov_b32 m0, s83
	s_nop 0
	buffer_load_dwordx4 v243, s[24:27], s4 offen lds
	s_waitcnt vmcnt(24)
	s_waitcnt lgkmcnt(0)
	s_barrier
	s_waitcnt lgkmcnt(7)
	v_mfma_f32_16x16x32_bf16 v[180:183], v[16:19], v[192:195], 0
	v_mfma_f32_16x16x32_bf16 v[164:167], v[24:27], v[192:195], 0
	s_waitcnt lgkmcnt(5)
	v_mfma_f32_16x16x32_bf16 v[148:151], v[16:19], v[200:203], 0
	v_mfma_f32_16x16x32_bf16 v[140:143], v[24:27], v[200:203], 0
	s_waitcnt lgkmcnt(3)
	v_mfma_f32_16x16x32_bf16 v[132:135], v[16:19], v[220:223], 0
	v_mfma_f32_16x16x32_bf16 v[124:127], v[24:27], v[220:223], 0
	s_waitcnt lgkmcnt(1)
	v_mfma_f32_16x16x32_bf16 v[116:119], v[16:19], v[228:231], 0
	v_mfma_f32_16x16x32_bf16 v[108:111], v[24:27], v[228:231], 0
	v_mfma_f32_16x16x32_bf16 v[180:183], v[20:23], v[196:199], v[180:183]
	v_mfma_f32_16x16x32_bf16 v[164:167], v[28:31], v[196:199], v[164:167]
	v_mfma_f32_16x16x32_bf16 v[148:151], v[20:23], v[204:207], v[148:151]
	v_mfma_f32_16x16x32_bf16 v[140:143], v[28:31], v[204:207], v[140:143]
	v_mfma_f32_16x16x32_bf16 v[132:135], v[20:23], v[224:227], v[132:135]
	v_mfma_f32_16x16x32_bf16 v[124:127], v[28:31], v[224:227], v[124:127]
	s_waitcnt lgkmcnt(0)
	v_mfma_f32_16x16x32_bf16 v[116:119], v[20:23], v[246:249], v[116:119]
	v_mfma_f32_16x16x32_bf16 v[108:111], v[28:31], v[246:249], v[108:111]
	v_mfma_f32_16x16x32_bf16 v[172:175], v[152:155], v[192:195], 0
	v_mfma_f32_16x16x32_bf16 v[156:159], v[168:171], v[192:195], 0
	v_mfma_f32_16x16x32_bf16 v[144:147], v[152:155], v[200:203], 0
	v_mfma_f32_16x16x32_bf16 v[136:139], v[168:171], v[200:203], 0
	v_mfma_f32_16x16x32_bf16 v[128:131], v[152:155], v[220:223], 0
	v_mfma_f32_16x16x32_bf16 v[120:123], v[168:171], v[220:223], 0
	v_mfma_f32_16x16x32_bf16 v[112:115], v[152:155], v[228:231], 0
	v_mfma_f32_16x16x32_bf16 v[104:107], v[168:171], v[228:231], 0
	v_mfma_f32_16x16x32_bf16 v[172:175], v[160:163], v[196:199], v[172:175]
	v_mfma_f32_16x16x32_bf16 v[156:159], v[176:179], v[196:199], v[156:159]
	v_mfma_f32_16x16x32_bf16 v[144:147], v[160:163], v[204:207], v[144:147]
	v_mfma_f32_16x16x32_bf16 v[136:139], v[176:179], v[204:207], v[136:139]
	v_mfma_f32_16x16x32_bf16 v[128:131], v[160:163], v[224:227], v[128:131]
	v_mfma_f32_16x16x32_bf16 v[120:123], v[176:179], v[224:227], v[120:123]
	v_mfma_f32_16x16x32_bf16 v[112:115], v[160:163], v[246:249], v[112:115]
	v_mfma_f32_16x16x32_bf16 v[104:107], v[176:179], v[246:249], v[104:107]
	s_barrier
	ds_read_b128 v[192:195], v245 offset:16384
	ds_read_b128 v[196:199], v245 offset:17408
	ds_read_b128 v[200:203], v245 offset:18432
	ds_read_b128 v[204:207], v245 offset:19456
	ds_read_b128 v[220:223], v245 offset:20480
	ds_read_b128 v[224:227], v245 offset:21504
	ds_read_b128 v[228:231], v245 offset:22528
	ds_read_b128 v[246:249], v245 offset:23552
	s_mov_b32 m0, s51
	s_nop 0
	buffer_load_dwordx4 v242, s[56:59], s16 offen lds
	s_add_i32 s18, s16, 0x80000
	s_mov_b32 m0, s52
	s_nop 0
	buffer_load_dwordx4 v243, s[56:59], s16 offen lds
	s_nop 7
	s_mov_b32 m0, s53
	s_nop 0
	buffer_load_dwordx4 v242, s[56:59], s18 offen lds
	s_nop 7
	s_mov_b32 m0, s55
	s_nop 0
	buffer_load_dwordx4 v243, s[56:59], s18 offen lds
	s_nop 7
	s_mov_b32 m0, s31
	s_nop 0
	buffer_load_dwordx4 v242, s[24:27], s17 offen lds
	s_nop 7
	s_mov_b32 m0, s68
	s_nop 0
	buffer_load_dwordx4 v243, s[24:27], s17 offen lds
	s_waitcnt vmcnt(24)
	s_waitcnt lgkmcnt(0)
	s_barrier
	s_waitcnt lgkmcnt(7)
	v_mfma_f32_16x16x32_bf16 v[76:79], v[16:19], v[192:195], 0
	v_mfma_f32_16x16x32_bf16 v[68:71], v[24:27], v[192:195], 0
	s_waitcnt lgkmcnt(5)
	v_mfma_f32_16x16x32_bf16 v[60:63], v[16:19], v[200:203], 0
	v_mfma_f32_16x16x32_bf16 v[52:55], v[24:27], v[200:203], 0
	s_waitcnt lgkmcnt(3)
	v_mfma_f32_16x16x32_bf16 v[44:47], v[16:19], v[220:223], 0
	v_mfma_f32_16x16x32_bf16 v[36:39], v[24:27], v[220:223], 0
	s_waitcnt lgkmcnt(1)
	v_mfma_f32_16x16x32_bf16 v[12:15], v[16:19], v[228:231], 0
	v_mfma_f32_16x16x32_bf16 v[4:7], v[24:27], v[228:231], 0
	v_mfma_f32_16x16x32_bf16 v[76:79], v[20:23], v[196:199], v[76:79]
	v_mfma_f32_16x16x32_bf16 v[68:71], v[28:31], v[196:199], v[68:71]
	v_mfma_f32_16x16x32_bf16 v[60:63], v[20:23], v[204:207], v[60:63]
	v_mfma_f32_16x16x32_bf16 v[52:55], v[28:31], v[204:207], v[52:55]
	v_mfma_f32_16x16x32_bf16 v[44:47], v[20:23], v[224:227], v[44:47]
	v_mfma_f32_16x16x32_bf16 v[36:39], v[28:31], v[224:227], v[36:39]
	s_waitcnt lgkmcnt(0)
	v_mfma_f32_16x16x32_bf16 v[12:15], v[20:23], v[246:249], v[12:15]
	v_mfma_f32_16x16x32_bf16 v[4:7], v[28:31], v[246:249], v[4:7]
	v_mfma_f32_16x16x32_bf16 v[40:43], v[152:155], v[220:223], 0
	v_mfma_f32_16x16x32_bf16 v[32:35], v[168:171], v[220:223], 0
	v_mfma_f32_16x16x32_bf16 v[8:11], v[152:155], v[228:231], 0
	v_mfma_f32_16x16x32_bf16 v[0:3], v[168:171], v[228:231], 0
	v_mfma_f32_16x16x32_bf16 v[16:19], v[152:155], v[192:195], 0
	v_mfma_f32_16x16x32_bf16 v[20:23], v[168:171], v[192:195], 0
	v_mfma_f32_16x16x32_bf16 v[24:27], v[152:155], v[200:203], 0
	v_mfma_f32_16x16x32_bf16 v[28:31], v[168:171], v[200:203], 0
	v_mfma_f32_16x16x32_bf16 v[40:43], v[160:163], v[224:227], v[40:43]
	v_mfma_f32_16x16x32_bf16 v[32:35], v[176:179], v[224:227], v[32:35]
	v_mfma_f32_16x16x32_bf16 v[8:11], v[160:163], v[246:249], v[8:11]
	v_mfma_f32_16x16x32_bf16 v[0:3], v[176:179], v[246:249], v[0:3]
	v_mfma_f32_16x16x32_bf16 v[16:19], v[160:163], v[196:199], v[16:19]
	v_mfma_f32_16x16x32_bf16 v[20:23], v[176:179], v[196:199], v[20:23]
	v_mfma_f32_16x16x32_bf16 v[24:27], v[160:163], v[204:207], v[24:27]
	v_mfma_f32_16x16x32_bf16 v[28:31], v[176:179], v[204:207], v[28:31]
	s_barrier
	v_add_u32_e32 v72, 0x18000, v83
	v_add_u32_e32 v80, 0x1c000, v83
	ds_read_b128 v[48:51], v72
	ds_read_b128 v[56:59], v72 offset:1024
	ds_read_b128 v[64:67], v72 offset:2048
	ds_read_b128 v[72:75], v72 offset:3072
	ds_read_b128 v[152:155], v80
	ds_read_b128 v[160:163], v80 offset:1024
	ds_read_b128 v[168:171], v80 offset:2048
	ds_read_b128 v[176:179], v80 offset:3072
	ds_read_b128 v[192:195], v245 offset:32768
	ds_read_b128 v[196:199], v245 offset:33792
	ds_read_b128 v[200:203], v245 offset:34816
	ds_read_b128 v[204:207], v245 offset:35840
	ds_read_b128 v[220:223], v245 offset:36864
	ds_read_b128 v[224:227], v245 offset:37888
	ds_read_b128 v[228:231], v245 offset:38912
	ds_read_b128 v[246:249], v245 offset:39936
	s_add_i32 s17, s17, 0x80000
	s_mov_b32 m0, s69
	s_nop 0
	buffer_load_dwordx4 v242, s[24:27], s17 offen lds
	s_nop 7
	s_mov_b32 m0, s70
	s_nop 0
	buffer_load_dwordx4 v243, s[24:27], s17 offen lds
	s_waitcnt vmcnt(8)
	s_waitcnt lgkmcnt(0)
	s_barrier
	s_waitcnt lgkmcnt(7)
	v_mfma_f32_16x16x32_bf16 v[180:183], v[48:51], v[192:195], v[180:183]
	v_mfma_f32_16x16x32_bf16 v[164:167], v[64:67], v[192:195], v[164:167]
	s_waitcnt lgkmcnt(5)
	v_mfma_f32_16x16x32_bf16 v[148:151], v[48:51], v[200:203], v[148:151]
	v_mfma_f32_16x16x32_bf16 v[140:143], v[64:67], v[200:203], v[140:143]
	s_waitcnt lgkmcnt(3)
	v_mfma_f32_16x16x32_bf16 v[132:135], v[48:51], v[220:223], v[132:135]
	v_mfma_f32_16x16x32_bf16 v[124:127], v[64:67], v[220:223], v[124:127]
	s_waitcnt lgkmcnt(1)
	v_mfma_f32_16x16x32_bf16 v[116:119], v[48:51], v[228:231], v[116:119]
	v_mfma_f32_16x16x32_bf16 v[108:111], v[64:67], v[228:231], v[108:111]
	v_mfma_f32_16x16x32_bf16 v[180:183], v[56:59], v[196:199], v[180:183]
	v_mfma_f32_16x16x32_bf16 v[164:167], v[72:75], v[196:199], v[164:167]
	v_mfma_f32_16x16x32_bf16 v[148:151], v[56:59], v[204:207], v[148:151]
	v_mfma_f32_16x16x32_bf16 v[140:143], v[72:75], v[204:207], v[140:143]
	v_mfma_f32_16x16x32_bf16 v[132:135], v[56:59], v[224:227], v[132:135]
	v_mfma_f32_16x16x32_bf16 v[124:127], v[72:75], v[224:227], v[124:127]
	s_waitcnt lgkmcnt(0)
	v_mfma_f32_16x16x32_bf16 v[116:119], v[56:59], v[246:249], v[116:119]
	v_mfma_f32_16x16x32_bf16 v[108:111], v[72:75], v[246:249], v[108:111]
	v_mfma_f32_16x16x32_bf16 v[172:175], v[152:155], v[192:195], v[172:175]
	v_mfma_f32_16x16x32_bf16 v[156:159], v[168:171], v[192:195], v[156:159]
	v_mfma_f32_16x16x32_bf16 v[144:147], v[152:155], v[200:203], v[144:147]
	v_mfma_f32_16x16x32_bf16 v[136:139], v[168:171], v[200:203], v[136:139]
	v_mfma_f32_16x16x32_bf16 v[128:131], v[152:155], v[220:223], v[128:131]
	v_mfma_f32_16x16x32_bf16 v[120:123], v[168:171], v[220:223], v[120:123]
	v_mfma_f32_16x16x32_bf16 v[112:115], v[152:155], v[228:231], v[112:115]
	v_mfma_f32_16x16x32_bf16 v[104:107], v[168:171], v[228:231], v[104:107]
	v_mfma_f32_16x16x32_bf16 v[172:175], v[160:163], v[196:199], v[172:175]
	v_mfma_f32_16x16x32_bf16 v[156:159], v[176:179], v[196:199], v[156:159]
	v_mfma_f32_16x16x32_bf16 v[144:147], v[160:163], v[204:207], v[144:147]
	v_mfma_f32_16x16x32_bf16 v[136:139], v[176:179], v[204:207], v[136:139]
	v_mfma_f32_16x16x32_bf16 v[128:131], v[160:163], v[224:227], v[128:131]
	v_mfma_f32_16x16x32_bf16 v[120:123], v[176:179], v[224:227], v[120:123]
	v_mfma_f32_16x16x32_bf16 v[112:115], v[160:163], v[246:249], v[112:115]
	v_mfma_f32_16x16x32_bf16 v[104:107], v[176:179], v[246:249], v[104:107]
	s_barrier
	ds_read_b128 v[192:195], v245 offset:49152
	ds_read_b128 v[196:199], v245 offset:50176
	ds_read_b128 v[200:203], v245 offset:51200
	ds_read_b128 v[204:207], v245 offset:52224
	ds_read_b128 v[220:223], v245 offset:53248
	ds_read_b128 v[224:227], v245 offset:54272
	ds_read_b128 v[228:231], v245 offset:55296
	ds_read_b128 v[246:249], v245 offset:56320
	s_or_b32 s17, s16, 0x4000
	s_mov_b32 m0, s73
	s_nop 0
	buffer_load_dwordx4 v242, s[56:59], s17 offen lds
	s_add_i32 s16, s16, 0x84000
	s_mov_b32 m0, s74
	s_nop 0
	buffer_load_dwordx4 v243, s[56:59], s17 offen lds
	s_nop 7
	s_mov_b32 m0, s77
	s_nop 0
	buffer_load_dwordx4 v242, s[56:59], s16 offen lds
	s_nop 7
	s_mov_b32 m0, s78
	s_nop 0
	buffer_load_dwordx4 v243, s[56:59], s16 offen lds
	s_nop 7
	s_mov_b32 m0, s75
	s_nop 0
	buffer_load_dwordx4 v242, s[24:27], s7 offen lds
	s_nop 7
	s_mov_b32 m0, s76
	s_nop 0
	buffer_load_dwordx4 v243, s[24:27], s7 offen lds
	s_waitcnt vmcnt(8)
	s_waitcnt lgkmcnt(0)
	s_barrier
	s_waitcnt lgkmcnt(7)
	v_mfma_f32_16x16x32_bf16 v[76:79], v[48:51], v[192:195], v[76:79]
	v_mfma_f32_16x16x32_bf16 v[68:71], v[64:67], v[192:195], v[68:71]
	s_waitcnt lgkmcnt(5)
	v_mfma_f32_16x16x32_bf16 v[60:63], v[48:51], v[200:203], v[60:63]
	v_mfma_f32_16x16x32_bf16 v[52:55], v[64:67], v[200:203], v[52:55]
	s_waitcnt lgkmcnt(3)
	v_mfma_f32_16x16x32_bf16 v[44:47], v[48:51], v[220:223], v[44:47]
	v_mfma_f32_16x16x32_bf16 v[36:39], v[64:67], v[220:223], v[36:39]
	s_waitcnt lgkmcnt(1)
	v_mfma_f32_16x16x32_bf16 v[12:15], v[48:51], v[228:231], v[12:15]
	v_mfma_f32_16x16x32_bf16 v[4:7], v[64:67], v[228:231], v[4:7]
	v_mfma_f32_16x16x32_bf16 v[76:79], v[56:59], v[196:199], v[76:79]
	v_mfma_f32_16x16x32_bf16 v[68:71], v[72:75], v[196:199], v[68:71]
	v_mfma_f32_16x16x32_bf16 v[60:63], v[56:59], v[204:207], v[60:63]
	v_mfma_f32_16x16x32_bf16 v[52:55], v[72:75], v[204:207], v[52:55]
	v_mfma_f32_16x16x32_bf16 v[44:47], v[56:59], v[224:227], v[44:47]
	v_mfma_f32_16x16x32_bf16 v[36:39], v[72:75], v[224:227], v[36:39]
	s_waitcnt lgkmcnt(0)
	v_mfma_f32_16x16x32_bf16 v[12:15], v[56:59], v[246:249], v[12:15]
	v_mfma_f32_16x16x32_bf16 v[4:7], v[72:75], v[246:249], v[4:7]
	v_mfma_f32_16x16x32_bf16 v[16:19], v[152:155], v[192:195], v[16:19]
	v_mfma_f32_16x16x32_bf16 v[72:75], v[160:163], v[196:199], v[16:19]
	v_mfma_f32_16x16x32_bf16 v[16:19], v[168:171], v[192:195], v[20:23]
	v_mfma_f32_16x16x32_bf16 v[64:67], v[176:179], v[196:199], v[16:19]
	v_mfma_f32_16x16x32_bf16 v[16:19], v[152:155], v[200:203], v[24:27]
	v_mfma_f32_16x16x32_bf16 v[56:59], v[160:163], v[204:207], v[16:19]
	v_mfma_f32_16x16x32_bf16 v[16:19], v[168:171], v[200:203], v[28:31]
	v_mfma_f32_16x16x32_bf16 v[48:51], v[176:179], v[204:207], v[16:19]
	v_mfma_f32_16x16x32_bf16 v[16:19], v[152:155], v[220:223], v[40:43]
	v_mfma_f32_16x16x32_bf16 v[40:43], v[160:163], v[224:227], v[16:19]
	v_mfma_f32_16x16x32_bf16 v[16:19], v[168:171], v[220:223], v[32:35]
	v_mfma_f32_16x16x32_bf16 v[8:11], v[152:155], v[228:231], v[8:11]
	v_mfma_f32_16x16x32_bf16 v[0:3], v[168:171], v[228:231], v[0:3]
	v_mfma_f32_16x16x32_bf16 v[32:35], v[176:179], v[224:227], v[16:19]
	v_mfma_f32_16x16x32_bf16 v[8:11], v[160:163], v[246:249], v[8:11]
	v_mfma_f32_16x16x32_bf16 v[0:3], v[176:179], v[246:249], v[0:3]
	s_barrier
	s_add_i32 s6, s6, 2
	s_add_i32 s4, s4, 0x8000
	s_add_i32 s5, s5, 0x8000
.LBB0_143:
	v_add_u32_e32 v28, 0x10000, v83
	v_add_u32_e32 v80, 0x14000, v83
	ds_read_b128 v[16:19], v28
	ds_read_b128 v[20:23], v28 offset:1024
	ds_read_b128 v[24:27], v28 offset:2048
	ds_read_b128 v[28:31], v28 offset:3072
	ds_read_b128 v[152:155], v80
	ds_read_b128 v[160:163], v80 offset:1024
	ds_read_b128 v[168:171], v80 offset:2048
	ds_read_b128 v[176:179], v80 offset:3072
	s_add_i32 s7, s4, 0xfff84000
	s_cmp_eq_u32 s6, 28
	s_cselect_b32 s17, s0, s7
	s_cselect_b32 s16, s1, s5
	s_or_b32 s7, s17, 0x4000
	ds_read_b128 v[192:195], v245
	ds_read_b128 v[196:199], v245 offset:1024
	ds_read_b128 v[200:203], v245 offset:2048
	ds_read_b128 v[204:207], v245 offset:3072
	ds_read_b128 v[220:223], v245 offset:4096
	ds_read_b128 v[224:227], v245 offset:5120
	ds_read_b128 v[228:231], v245 offset:6144
	ds_read_b128 v[246:249], v245 offset:7168
	s_mov_b32 m0, s79
	s_nop 0
	buffer_load_dwordx4 v242, s[24:27], s4 offen lds
	s_nop 7
	s_mov_b32 m0, s83
	s_nop 0
	buffer_load_dwordx4 v243, s[24:27], s4 offen lds
	s_waitcnt vmcnt(8)
	s_waitcnt lgkmcnt(0)
	s_barrier
	s_waitcnt lgkmcnt(7)
	v_mfma_f32_16x16x32_bf16 v[180:183], v[16:19], v[192:195], v[180:183]
	v_mfma_f32_16x16x32_bf16 v[164:167], v[24:27], v[192:195], v[164:167]
	s_waitcnt lgkmcnt(5)
	v_mfma_f32_16x16x32_bf16 v[148:151], v[16:19], v[200:203], v[148:151]
	v_mfma_f32_16x16x32_bf16 v[140:143], v[24:27], v[200:203], v[140:143]
	s_waitcnt lgkmcnt(3)
	v_mfma_f32_16x16x32_bf16 v[132:135], v[16:19], v[220:223], v[132:135]
	v_mfma_f32_16x16x32_bf16 v[124:127], v[24:27], v[220:223], v[124:127]
	s_waitcnt lgkmcnt(1)
	v_mfma_f32_16x16x32_bf16 v[116:119], v[16:19], v[228:231], v[116:119]
	v_mfma_f32_16x16x32_bf16 v[108:111], v[24:27], v[228:231], v[108:111]
	v_mfma_f32_16x16x32_bf16 v[180:183], v[20:23], v[196:199], v[180:183]
	v_mfma_f32_16x16x32_bf16 v[164:167], v[28:31], v[196:199], v[164:167]
	v_mfma_f32_16x16x32_bf16 v[148:151], v[20:23], v[204:207], v[148:151]
	v_mfma_f32_16x16x32_bf16 v[140:143], v[28:31], v[204:207], v[140:143]
	v_mfma_f32_16x16x32_bf16 v[132:135], v[20:23], v[224:227], v[132:135]
	v_mfma_f32_16x16x32_bf16 v[124:127], v[28:31], v[224:227], v[124:127]
	s_waitcnt lgkmcnt(0)
	v_mfma_f32_16x16x32_bf16 v[116:119], v[20:23], v[246:249], v[116:119]
	v_mfma_f32_16x16x32_bf16 v[108:111], v[28:31], v[246:249], v[108:111]
	v_mfma_f32_16x16x32_bf16 v[172:175], v[152:155], v[192:195], v[172:175]
	v_mfma_f32_16x16x32_bf16 v[156:159], v[168:171], v[192:195], v[156:159]
	v_mfma_f32_16x16x32_bf16 v[144:147], v[152:155], v[200:203], v[144:147]
	v_mfma_f32_16x16x32_bf16 v[136:139], v[168:171], v[200:203], v[136:139]
	v_mfma_f32_16x16x32_bf16 v[128:131], v[152:155], v[220:223], v[128:131]
	v_mfma_f32_16x16x32_bf16 v[120:123], v[168:171], v[220:223], v[120:123]
	v_mfma_f32_16x16x32_bf16 v[112:115], v[152:155], v[228:231], v[112:115]
	v_mfma_f32_16x16x32_bf16 v[104:107], v[168:171], v[228:231], v[104:107]
	v_mfma_f32_16x16x32_bf16 v[172:175], v[160:163], v[196:199], v[172:175]
	v_mfma_f32_16x16x32_bf16 v[156:159], v[176:179], v[196:199], v[156:159]
	v_mfma_f32_16x16x32_bf16 v[144:147], v[160:163], v[204:207], v[144:147]
	v_mfma_f32_16x16x32_bf16 v[136:139], v[176:179], v[204:207], v[136:139]
	v_mfma_f32_16x16x32_bf16 v[128:131], v[160:163], v[224:227], v[128:131]
	v_mfma_f32_16x16x32_bf16 v[120:123], v[176:179], v[224:227], v[120:123]
	v_mfma_f32_16x16x32_bf16 v[112:115], v[160:163], v[246:249], v[112:115]
	v_mfma_f32_16x16x32_bf16 v[104:107], v[176:179], v[246:249], v[104:107]
	s_barrier
	ds_read_b128 v[192:195], v245 offset:16384
	ds_read_b128 v[196:199], v245 offset:17408
	ds_read_b128 v[200:203], v245 offset:18432
	ds_read_b128 v[204:207], v245 offset:19456
	ds_read_b128 v[220:223], v245 offset:20480
	ds_read_b128 v[224:227], v245 offset:21504
	ds_read_b128 v[228:231], v245 offset:22528
	ds_read_b128 v[246:249], v245 offset:23552
	s_mov_b32 m0, s51
	s_nop 0
	buffer_load_dwordx4 v242, s[56:59], s16 offen lds
	s_add_i32 s18, s16, 0x80000
	s_mov_b32 m0, s52
	s_nop 0
	buffer_load_dwordx4 v243, s[56:59], s16 offen lds
	s_nop 7
	s_mov_b32 m0, s53
	s_nop 0
	buffer_load_dwordx4 v242, s[56:59], s18 offen lds
	s_nop 7
	s_mov_b32 m0, s55
	s_nop 0
	buffer_load_dwordx4 v243, s[56:59], s18 offen lds
	s_nop 7
	s_mov_b32 m0, s31
	s_nop 0
	buffer_load_dwordx4 v242, s[24:27], s17 offen lds
	s_nop 7
	s_mov_b32 m0, s68
	s_nop 0
	buffer_load_dwordx4 v243, s[24:27], s17 offen lds
	s_waitcnt vmcnt(8)
	s_waitcnt lgkmcnt(0)
	s_barrier
	s_waitcnt lgkmcnt(7)
	v_mfma_f32_16x16x32_bf16 v[76:79], v[16:19], v[192:195], v[76:79]
	v_mfma_f32_16x16x32_bf16 v[68:71], v[24:27], v[192:195], v[68:71]
	s_waitcnt lgkmcnt(5)
	v_mfma_f32_16x16x32_bf16 v[60:63], v[16:19], v[200:203], v[60:63]
	v_mfma_f32_16x16x32_bf16 v[52:55], v[24:27], v[200:203], v[52:55]
	s_waitcnt lgkmcnt(3)
	v_mfma_f32_16x16x32_bf16 v[44:47], v[16:19], v[220:223], v[44:47]
	v_mfma_f32_16x16x32_bf16 v[36:39], v[24:27], v[220:223], v[36:39]
	s_waitcnt lgkmcnt(1)
	v_mfma_f32_16x16x32_bf16 v[12:15], v[16:19], v[228:231], v[12:15]
	v_mfma_f32_16x16x32_bf16 v[4:7], v[24:27], v[228:231], v[4:7]
	v_mfma_f32_16x16x32_bf16 v[76:79], v[20:23], v[196:199], v[76:79]
	v_mfma_f32_16x16x32_bf16 v[68:71], v[28:31], v[196:199], v[68:71]
	v_mfma_f32_16x16x32_bf16 v[60:63], v[20:23], v[204:207], v[60:63]
	v_mfma_f32_16x16x32_bf16 v[52:55], v[28:31], v[204:207], v[52:55]
	v_mfma_f32_16x16x32_bf16 v[44:47], v[20:23], v[224:227], v[44:47]
	v_mfma_f32_16x16x32_bf16 v[36:39], v[28:31], v[224:227], v[36:39]
	s_waitcnt lgkmcnt(0)
	v_mfma_f32_16x16x32_bf16 v[12:15], v[20:23], v[246:249], v[12:15]
	v_mfma_f32_16x16x32_bf16 v[4:7], v[28:31], v[246:249], v[4:7]
	v_mfma_f32_16x16x32_bf16 v[40:43], v[152:155], v[220:223], v[40:43]
	v_mfma_f32_16x16x32_bf16 v[32:35], v[168:171], v[220:223], v[32:35]
	v_mfma_f32_16x16x32_bf16 v[8:11], v[152:155], v[228:231], v[8:11]
	v_mfma_f32_16x16x32_bf16 v[0:3], v[168:171], v[228:231], v[0:3]
	v_mfma_f32_16x16x32_bf16 v[16:19], v[152:155], v[192:195], v[72:75]
	v_mfma_f32_16x16x32_bf16 v[20:23], v[168:171], v[192:195], v[64:67]
	v_mfma_f32_16x16x32_bf16 v[24:27], v[152:155], v[200:203], v[56:59]
	v_mfma_f32_16x16x32_bf16 v[28:31], v[168:171], v[200:203], v[48:51]
	v_mfma_f32_16x16x32_bf16 v[40:43], v[160:163], v[224:227], v[40:43]
	v_mfma_f32_16x16x32_bf16 v[32:35], v[176:179], v[224:227], v[32:35]
	v_mfma_f32_16x16x32_bf16 v[8:11], v[160:163], v[246:249], v[8:11]
	v_mfma_f32_16x16x32_bf16 v[0:3], v[176:179], v[246:249], v[0:3]
	v_mfma_f32_16x16x32_bf16 v[16:19], v[160:163], v[196:199], v[16:19]
	v_mfma_f32_16x16x32_bf16 v[20:23], v[176:179], v[196:199], v[20:23]
	v_mfma_f32_16x16x32_bf16 v[24:27], v[160:163], v[204:207], v[24:27]
	v_mfma_f32_16x16x32_bf16 v[28:31], v[176:179], v[204:207], v[28:31]
	s_barrier
	v_add_u32_e32 v72, 0x18000, v83
	v_add_u32_e32 v80, 0x1c000, v83
	ds_read_b128 v[48:51], v72
	ds_read_b128 v[56:59], v72 offset:1024
	ds_read_b128 v[64:67], v72 offset:2048
	ds_read_b128 v[72:75], v72 offset:3072
	ds_read_b128 v[152:155], v80
	ds_read_b128 v[160:163], v80 offset:1024
	ds_read_b128 v[168:171], v80 offset:2048
	ds_read_b128 v[176:179], v80 offset:3072
	ds_read_b128 v[192:195], v245 offset:32768
	ds_read_b128 v[196:199], v245 offset:33792
	ds_read_b128 v[200:203], v245 offset:34816
	ds_read_b128 v[204:207], v245 offset:35840
	ds_read_b128 v[220:223], v245 offset:36864
	ds_read_b128 v[224:227], v245 offset:37888
	ds_read_b128 v[228:231], v245 offset:38912
	ds_read_b128 v[246:249], v245 offset:39936
	s_add_i32 s17, s17, 0x80000
	s_mov_b32 m0, s69
	s_nop 0
	buffer_load_dwordx4 v242, s[24:27], s17 offen lds
	s_nop 7
	s_mov_b32 m0, s70
	s_nop 0
	buffer_load_dwordx4 v243, s[24:27], s17 offen lds
	s_waitcnt vmcnt(8)
	s_waitcnt lgkmcnt(0)
	s_barrier
	s_waitcnt lgkmcnt(7)
	v_mfma_f32_16x16x32_bf16 v[180:183], v[48:51], v[192:195], v[180:183]
	v_mfma_f32_16x16x32_bf16 v[164:167], v[64:67], v[192:195], v[164:167]
	s_waitcnt lgkmcnt(5)
	v_mfma_f32_16x16x32_bf16 v[148:151], v[48:51], v[200:203], v[148:151]
	v_mfma_f32_16x16x32_bf16 v[140:143], v[64:67], v[200:203], v[140:143]
	s_waitcnt lgkmcnt(3)
	v_mfma_f32_16x16x32_bf16 v[132:135], v[48:51], v[220:223], v[132:135]
	v_mfma_f32_16x16x32_bf16 v[124:127], v[64:67], v[220:223], v[124:127]
	s_waitcnt lgkmcnt(1)
	v_mfma_f32_16x16x32_bf16 v[116:119], v[48:51], v[228:231], v[116:119]
	v_mfma_f32_16x16x32_bf16 v[108:111], v[64:67], v[228:231], v[108:111]
	v_mfma_f32_16x16x32_bf16 v[180:183], v[56:59], v[196:199], v[180:183]
	v_mfma_f32_16x16x32_bf16 v[164:167], v[72:75], v[196:199], v[164:167]
	v_mfma_f32_16x16x32_bf16 v[148:151], v[56:59], v[204:207], v[148:151]
	v_mfma_f32_16x16x32_bf16 v[140:143], v[72:75], v[204:207], v[140:143]
	v_mfma_f32_16x16x32_bf16 v[132:135], v[56:59], v[224:227], v[132:135]
	v_mfma_f32_16x16x32_bf16 v[124:127], v[72:75], v[224:227], v[124:127]
	s_waitcnt lgkmcnt(0)
	v_mfma_f32_16x16x32_bf16 v[116:119], v[56:59], v[246:249], v[116:119]
	v_mfma_f32_16x16x32_bf16 v[108:111], v[72:75], v[246:249], v[108:111]
	v_mfma_f32_16x16x32_bf16 v[172:175], v[152:155], v[192:195], v[172:175]
	v_mfma_f32_16x16x32_bf16 v[156:159], v[168:171], v[192:195], v[156:159]
	v_mfma_f32_16x16x32_bf16 v[144:147], v[152:155], v[200:203], v[144:147]
	v_mfma_f32_16x16x32_bf16 v[136:139], v[168:171], v[200:203], v[136:139]
	v_mfma_f32_16x16x32_bf16 v[128:131], v[152:155], v[220:223], v[128:131]
	v_mfma_f32_16x16x32_bf16 v[120:123], v[168:171], v[220:223], v[120:123]
	v_mfma_f32_16x16x32_bf16 v[112:115], v[152:155], v[228:231], v[112:115]
	v_mfma_f32_16x16x32_bf16 v[104:107], v[168:171], v[228:231], v[104:107]
	v_mfma_f32_16x16x32_bf16 v[172:175], v[160:163], v[196:199], v[172:175]
	v_mfma_f32_16x16x32_bf16 v[156:159], v[176:179], v[196:199], v[156:159]
	v_mfma_f32_16x16x32_bf16 v[144:147], v[160:163], v[204:207], v[144:147]
	v_mfma_f32_16x16x32_bf16 v[136:139], v[176:179], v[204:207], v[136:139]
	v_mfma_f32_16x16x32_bf16 v[128:131], v[160:163], v[224:227], v[128:131]
	v_mfma_f32_16x16x32_bf16 v[120:123], v[176:179], v[224:227], v[120:123]
	v_mfma_f32_16x16x32_bf16 v[112:115], v[160:163], v[246:249], v[112:115]
	v_mfma_f32_16x16x32_bf16 v[104:107], v[176:179], v[246:249], v[104:107]
	s_barrier
	ds_read_b128 v[192:195], v245 offset:49152
	ds_read_b128 v[196:199], v245 offset:50176
	ds_read_b128 v[200:203], v245 offset:51200
	ds_read_b128 v[204:207], v245 offset:52224
	ds_read_b128 v[220:223], v245 offset:53248
	ds_read_b128 v[224:227], v245 offset:54272
	ds_read_b128 v[228:231], v245 offset:55296
	ds_read_b128 v[246:249], v245 offset:56320
	s_or_b32 s17, s16, 0x4000
	s_mov_b32 m0, s73
	s_nop 0
	buffer_load_dwordx4 v242, s[56:59], s17 offen lds
	s_add_i32 s16, s16, 0x84000
	s_mov_b32 m0, s74
	s_nop 0
	buffer_load_dwordx4 v243, s[56:59], s17 offen lds
	s_nop 7
	s_mov_b32 m0, s77
	s_nop 0
	buffer_load_dwordx4 v242, s[56:59], s16 offen lds
	s_nop 7
	s_mov_b32 m0, s78
	s_nop 0
	buffer_load_dwordx4 v243, s[56:59], s16 offen lds
	s_nop 7
	s_mov_b32 m0, s75
	s_nop 0
	buffer_load_dwordx4 v242, s[24:27], s7 offen lds
	s_nop 7
	s_mov_b32 m0, s76
	s_nop 0
	buffer_load_dwordx4 v243, s[24:27], s7 offen lds
	s_waitcnt vmcnt(8)
	s_waitcnt lgkmcnt(0)
	s_barrier
	s_waitcnt lgkmcnt(7)
	v_mfma_f32_16x16x32_bf16 v[76:79], v[48:51], v[192:195], v[76:79]
	v_mfma_f32_16x16x32_bf16 v[68:71], v[64:67], v[192:195], v[68:71]
	s_waitcnt lgkmcnt(5)
	v_mfma_f32_16x16x32_bf16 v[60:63], v[48:51], v[200:203], v[60:63]
	v_mfma_f32_16x16x32_bf16 v[52:55], v[64:67], v[200:203], v[52:55]
	s_waitcnt lgkmcnt(3)
	v_mfma_f32_16x16x32_bf16 v[44:47], v[48:51], v[220:223], v[44:47]
	v_mfma_f32_16x16x32_bf16 v[36:39], v[64:67], v[220:223], v[36:39]
	s_waitcnt lgkmcnt(1)
	v_mfma_f32_16x16x32_bf16 v[12:15], v[48:51], v[228:231], v[12:15]
	v_mfma_f32_16x16x32_bf16 v[4:7], v[64:67], v[228:231], v[4:7]
	v_mfma_f32_16x16x32_bf16 v[76:79], v[56:59], v[196:199], v[76:79]
	v_mfma_f32_16x16x32_bf16 v[68:71], v[72:75], v[196:199], v[68:71]
	v_mfma_f32_16x16x32_bf16 v[60:63], v[56:59], v[204:207], v[60:63]
	v_mfma_f32_16x16x32_bf16 v[52:55], v[72:75], v[204:207], v[52:55]
	v_mfma_f32_16x16x32_bf16 v[44:47], v[56:59], v[224:227], v[44:47]
	v_mfma_f32_16x16x32_bf16 v[36:39], v[72:75], v[224:227], v[36:39]
	s_waitcnt lgkmcnt(0)
	v_mfma_f32_16x16x32_bf16 v[12:15], v[56:59], v[246:249], v[12:15]
	v_mfma_f32_16x16x32_bf16 v[4:7], v[72:75], v[246:249], v[4:7]
	v_mfma_f32_16x16x32_bf16 v[16:19], v[152:155], v[192:195], v[16:19]
	v_mfma_f32_16x16x32_bf16 v[72:75], v[160:163], v[196:199], v[16:19]
	v_mfma_f32_16x16x32_bf16 v[16:19], v[168:171], v[192:195], v[20:23]
	v_mfma_f32_16x16x32_bf16 v[64:67], v[176:179], v[196:199], v[16:19]
	v_mfma_f32_16x16x32_bf16 v[16:19], v[152:155], v[200:203], v[24:27]
	v_mfma_f32_16x16x32_bf16 v[56:59], v[160:163], v[204:207], v[16:19]
	v_mfma_f32_16x16x32_bf16 v[16:19], v[168:171], v[200:203], v[28:31]
	v_mfma_f32_16x16x32_bf16 v[48:51], v[176:179], v[204:207], v[16:19]
	v_mfma_f32_16x16x32_bf16 v[16:19], v[152:155], v[220:223], v[40:43]
	v_mfma_f32_16x16x32_bf16 v[40:43], v[160:163], v[224:227], v[16:19]
	v_mfma_f32_16x16x32_bf16 v[16:19], v[168:171], v[220:223], v[32:35]
	v_mfma_f32_16x16x32_bf16 v[8:11], v[152:155], v[228:231], v[8:11]
	v_mfma_f32_16x16x32_bf16 v[0:3], v[168:171], v[228:231], v[0:3]
	v_mfma_f32_16x16x32_bf16 v[32:35], v[176:179], v[224:227], v[16:19]
	v_mfma_f32_16x16x32_bf16 v[8:11], v[160:163], v[246:249], v[8:11]
	v_mfma_f32_16x16x32_bf16 v[0:3], v[176:179], v[246:249], v[0:3]
	s_barrier
	s_add_i32 s6, s6, 2
	s_add_i32 s4, s4, 0x8000
	s_add_i32 s5, s5, 0x8000
	s_cmp_gt_u32 s6, 29
	s_cbranch_scc0 .LBB0_143

.LBB0_594:
	v_add_u32_e32 v80, 0x10000, v226
	ds_read_b128 v[152:155], v80
	ds_read_b128 v[156:159], v80 offset:1024
	ds_read_b128 v[160:163], v80 offset:2048
	ds_read_b128 v[164:167], v80 offset:3072
	v_add_u32_e32 v80, 0x14000, v226
	ds_read_b128 v[168:171], v80
	ds_read_b128 v[172:175], v80 offset:1024
	ds_read_b128 v[176:179], v80 offset:2048
	ds_read_b128 v[180:183], v80 offset:3072
	s_add_i32 s97, s96, s39
	s_add_i32 s94, s97, 0x8000
	s_add_i32 s95, s93, s39
	s_cmp_eq_u32 s39, 0x78000
	s_cselect_b32 s36, vcc_lo, s94
	s_cselect_b32 s95, vcc_hi, s95
	s_or_b32 s94, s36, 0x4000
	ds_read_b128 v[184:187], v227
	ds_read_b128 v[188:191], v227 offset:1024
	ds_read_b128 v[192:195], v227 offset:2048
	ds_read_b128 v[196:199], v227 offset:3072
	ds_read_b128 v[200:203], v227 offset:4096
	ds_read_b128 v[204:207], v227 offset:5120
	ds_read_b128 v[228:231], v227 offset:6144
	ds_read_b128 v[240:243], v227 offset:7168
	s_add_i32 s97, s97, 0x84000
	s_mov_b32 m0, s85
	s_nop 0
	buffer_load_dwordx4 v224, s[60:63], s97 offen lds
	s_nop 7
	s_mov_b32 m0, s86
	s_nop 0
	buffer_load_dwordx4 v225, s[60:63], s97 offen lds
	s_waitcnt vmcnt(8)
	s_waitcnt lgkmcnt(0)
	s_barrier
	s_waitcnt lgkmcnt(7)
	v_mfma_f32_16x16x32_bf16 v[148:151], v[152:155], v[184:187], v[148:151]
	v_mfma_f32_16x16x32_bf16 v[144:147], v[160:163], v[184:187], v[144:147]
	s_waitcnt lgkmcnt(5)
	v_mfma_f32_16x16x32_bf16 v[132:135], v[152:155], v[192:195], v[132:135]
	v_mfma_f32_16x16x32_bf16 v[128:131], v[160:163], v[192:195], v[128:131]
	s_waitcnt lgkmcnt(3)
	v_mfma_f32_16x16x32_bf16 v[116:119], v[152:155], v[200:203], v[116:119]
	v_mfma_f32_16x16x32_bf16 v[112:115], v[160:163], v[200:203], v[112:115]
	s_waitcnt lgkmcnt(1)
	v_mfma_f32_16x16x32_bf16 v[76:79], v[152:155], v[228:231], v[76:79]
	v_mfma_f32_16x16x32_bf16 v[72:75], v[160:163], v[228:231], v[72:75]
	v_mfma_f32_16x16x32_bf16 v[148:151], v[156:159], v[188:191], v[148:151]
	v_mfma_f32_16x16x32_bf16 v[144:147], v[164:167], v[188:191], v[144:147]
	v_mfma_f32_16x16x32_bf16 v[132:135], v[156:159], v[196:199], v[132:135]
	v_mfma_f32_16x16x32_bf16 v[128:131], v[164:167], v[196:199], v[128:131]
	v_mfma_f32_16x16x32_bf16 v[116:119], v[156:159], v[204:207], v[116:119]
	v_mfma_f32_16x16x32_bf16 v[112:115], v[164:167], v[204:207], v[112:115]
	s_waitcnt lgkmcnt(0)
	v_mfma_f32_16x16x32_bf16 v[76:79], v[156:159], v[240:243], v[76:79]
	v_mfma_f32_16x16x32_bf16 v[72:75], v[164:167], v[240:243], v[72:75]
	v_mfma_f32_16x16x32_bf16 v[140:143], v[168:171], v[184:187], v[140:143]
	v_mfma_f32_16x16x32_bf16 v[136:139], v[176:179], v[184:187], v[136:139]
	v_mfma_f32_16x16x32_bf16 v[124:127], v[168:171], v[192:195], v[124:127]
	v_mfma_f32_16x16x32_bf16 v[120:123], v[176:179], v[192:195], v[120:123]
	v_mfma_f32_16x16x32_bf16 v[108:111], v[168:171], v[200:203], v[108:111]
	v_mfma_f32_16x16x32_bf16 v[104:107], v[176:179], v[200:203], v[104:107]
	v_mfma_f32_16x16x32_bf16 v[68:71], v[168:171], v[228:231], v[68:71]
	v_mfma_f32_16x16x32_bf16 v[64:67], v[176:179], v[228:231], v[64:67]
	v_mfma_f32_16x16x32_bf16 v[140:143], v[172:175], v[188:191], v[140:143]
	v_mfma_f32_16x16x32_bf16 v[136:139], v[180:183], v[188:191], v[136:139]
	v_mfma_f32_16x16x32_bf16 v[124:127], v[172:175], v[196:199], v[124:127]
	v_mfma_f32_16x16x32_bf16 v[120:123], v[180:183], v[196:199], v[120:123]
	v_mfma_f32_16x16x32_bf16 v[108:111], v[172:175], v[204:207], v[108:111]
	v_mfma_f32_16x16x32_bf16 v[104:107], v[180:183], v[204:207], v[104:107]
	v_mfma_f32_16x16x32_bf16 v[68:71], v[172:175], v[240:243], v[68:71]
	v_mfma_f32_16x16x32_bf16 v[64:67], v[180:183], v[240:243], v[64:67]
	s_barrier
	ds_read_b128 v[184:187], v227 offset:16384
	ds_read_b128 v[188:191], v227 offset:17408
	ds_read_b128 v[192:195], v227 offset:18432
	ds_read_b128 v[196:199], v227 offset:19456
	ds_read_b128 v[200:203], v227 offset:20480
	ds_read_b128 v[204:207], v227 offset:21504
	ds_read_b128 v[228:231], v227 offset:22528
	ds_read_b128 v[240:243], v227 offset:23552
	s_mov_b32 m0, s34
	s_nop 0
	buffer_load_dwordx4 v224, s[48:51], s95 offen lds
	s_add_i32 s97, s95, 0x80000
	s_mov_b32 m0, s55
	s_nop 0
	buffer_load_dwordx4 v225, s[48:51], s95 offen lds
	s_nop 7
	s_mov_b32 m0, s72
	s_nop 0
	buffer_load_dwordx4 v224, s[48:51], s97 offen lds
	s_nop 7
	s_mov_b32 m0, s73
	s_nop 0
	buffer_load_dwordx4 v225, s[48:51], s97 offen lds
	s_nop 7
	s_mov_b32 m0, s31
	s_nop 0
	buffer_load_dwordx4 v224, s[60:63], s36 offen lds
	s_nop 7
	s_mov_b32 m0, s74
	s_nop 0
	buffer_load_dwordx4 v225, s[60:63], s36 offen lds
	s_waitcnt vmcnt(8)
	s_waitcnt lgkmcnt(0)
	s_barrier
	s_waitcnt lgkmcnt(7)
	v_mfma_f32_16x16x32_bf16 v[60:63], v[152:155], v[184:187], v[60:63]
	v_mfma_f32_16x16x32_bf16 v[56:59], v[160:163], v[184:187], v[56:59]
	s_waitcnt lgkmcnt(5)
	v_mfma_f32_16x16x32_bf16 v[44:47], v[152:155], v[192:195], v[44:47]
	v_mfma_f32_16x16x32_bf16 v[40:43], v[160:163], v[192:195], v[40:43]
	s_waitcnt lgkmcnt(3)
	v_mfma_f32_16x16x32_bf16 v[28:31], v[152:155], v[200:203], v[28:31]
	v_mfma_f32_16x16x32_bf16 v[24:27], v[160:163], v[200:203], v[24:27]
	s_waitcnt lgkmcnt(1)
	v_mfma_f32_16x16x32_bf16 v[12:15], v[152:155], v[228:231], v[12:15]
	v_mfma_f32_16x16x32_bf16 v[8:11], v[160:163], v[228:231], v[8:11]
	v_mfma_f32_16x16x32_bf16 v[60:63], v[156:159], v[188:191], v[60:63]
	v_mfma_f32_16x16x32_bf16 v[56:59], v[164:167], v[188:191], v[56:59]
	v_mfma_f32_16x16x32_bf16 v[44:47], v[156:159], v[196:199], v[44:47]
	v_mfma_f32_16x16x32_bf16 v[40:43], v[164:167], v[196:199], v[40:43]
	v_mfma_f32_16x16x32_bf16 v[28:31], v[156:159], v[204:207], v[28:31]
	v_mfma_f32_16x16x32_bf16 v[24:27], v[164:167], v[204:207], v[24:27]
	s_waitcnt lgkmcnt(0)
	v_mfma_f32_16x16x32_bf16 v[12:15], v[156:159], v[240:243], v[12:15]
	v_mfma_f32_16x16x32_bf16 v[8:11], v[164:167], v[240:243], v[8:11]
	v_mfma_f32_16x16x32_bf16 v[52:55], v[168:171], v[184:187], v[52:55]
	v_mfma_f32_16x16x32_bf16 v[48:51], v[176:179], v[184:187], v[48:51]
	v_mfma_f32_16x16x32_bf16 v[36:39], v[168:171], v[192:195], v[36:39]
	v_mfma_f32_16x16x32_bf16 v[32:35], v[176:179], v[192:195], v[32:35]
	v_mfma_f32_16x16x32_bf16 v[20:23], v[168:171], v[200:203], v[20:23]
	v_mfma_f32_16x16x32_bf16 v[16:19], v[176:179], v[200:203], v[16:19]
	v_mfma_f32_16x16x32_bf16 v[4:7], v[168:171], v[228:231], v[4:7]
	v_mfma_f32_16x16x32_bf16 v[0:3], v[176:179], v[228:231], v[0:3]
	v_mfma_f32_16x16x32_bf16 v[52:55], v[172:175], v[188:191], v[52:55]
	v_mfma_f32_16x16x32_bf16 v[48:51], v[180:183], v[188:191], v[48:51]
	v_mfma_f32_16x16x32_bf16 v[36:39], v[172:175], v[196:199], v[36:39]
	v_mfma_f32_16x16x32_bf16 v[32:35], v[180:183], v[196:199], v[32:35]
	v_mfma_f32_16x16x32_bf16 v[20:23], v[172:175], v[204:207], v[20:23]
	v_mfma_f32_16x16x32_bf16 v[16:19], v[180:183], v[204:207], v[16:19]
	v_mfma_f32_16x16x32_bf16 v[4:7], v[172:175], v[240:243], v[4:7]
	v_mfma_f32_16x16x32_bf16 v[0:3], v[180:183], v[240:243], v[0:3]
	s_barrier
	v_add_u32_e32 v80, 0x18000, v226
	ds_read_b128 v[152:155], v80
	ds_read_b128 v[156:159], v80 offset:1024
	ds_read_b128 v[160:163], v80 offset:2048
	ds_read_b128 v[164:167], v80 offset:3072
	v_add_u32_e32 v80, 0x1c000, v226
	ds_read_b128 v[168:171], v80
	ds_read_b128 v[172:175], v80 offset:1024
	ds_read_b128 v[176:179], v80 offset:2048
	ds_read_b128 v[180:183], v80 offset:3072
	ds_read_b128 v[184:187], v227 offset:32768
	ds_read_b128 v[188:191], v227 offset:33792
	ds_read_b128 v[192:195], v227 offset:34816
	ds_read_b128 v[196:199], v227 offset:35840
	ds_read_b128 v[200:203], v227 offset:36864
	ds_read_b128 v[204:207], v227 offset:37888
	ds_read_b128 v[228:231], v227 offset:38912
	ds_read_b128 v[240:243], v227 offset:39936
	s_add_i32 s36, s36, 0x80000
	s_mov_b32 m0, s75
	s_nop 0
	buffer_load_dwordx4 v224, s[60:63], s36 offen lds
	s_nop 7
	s_mov_b32 m0, s76
	s_nop 0
	buffer_load_dwordx4 v225, s[60:63], s36 offen lds
	s_waitcnt vmcnt(8)
	s_waitcnt lgkmcnt(0)
	s_barrier
	s_waitcnt lgkmcnt(7)
	v_mfma_f32_16x16x32_bf16 v[148:151], v[152:155], v[184:187], v[148:151]
	v_mfma_f32_16x16x32_bf16 v[144:147], v[160:163], v[184:187], v[144:147]
	s_waitcnt lgkmcnt(5)
	v_mfma_f32_16x16x32_bf16 v[132:135], v[152:155], v[192:195], v[132:135]
	v_mfma_f32_16x16x32_bf16 v[128:131], v[160:163], v[192:195], v[128:131]
	s_waitcnt lgkmcnt(3)
	v_mfma_f32_16x16x32_bf16 v[116:119], v[152:155], v[200:203], v[116:119]
	v_mfma_f32_16x16x32_bf16 v[112:115], v[160:163], v[200:203], v[112:115]
	s_waitcnt lgkmcnt(1)
	v_mfma_f32_16x16x32_bf16 v[76:79], v[152:155], v[228:231], v[76:79]
	v_mfma_f32_16x16x32_bf16 v[72:75], v[160:163], v[228:231], v[72:75]
	v_mfma_f32_16x16x32_bf16 v[148:151], v[156:159], v[188:191], v[148:151]
	v_mfma_f32_16x16x32_bf16 v[144:147], v[164:167], v[188:191], v[144:147]
	v_mfma_f32_16x16x32_bf16 v[132:135], v[156:159], v[196:199], v[132:135]
	v_mfma_f32_16x16x32_bf16 v[128:131], v[164:167], v[196:199], v[128:131]
	v_mfma_f32_16x16x32_bf16 v[116:119], v[156:159], v[204:207], v[116:119]
	v_mfma_f32_16x16x32_bf16 v[112:115], v[164:167], v[204:207], v[112:115]
	s_waitcnt lgkmcnt(0)
	v_mfma_f32_16x16x32_bf16 v[76:79], v[156:159], v[240:243], v[76:79]
	v_mfma_f32_16x16x32_bf16 v[72:75], v[164:167], v[240:243], v[72:75]
	v_mfma_f32_16x16x32_bf16 v[140:143], v[168:171], v[184:187], v[140:143]
	v_mfma_f32_16x16x32_bf16 v[136:139], v[176:179], v[184:187], v[136:139]
	v_mfma_f32_16x16x32_bf16 v[124:127], v[168:171], v[192:195], v[124:127]
	v_mfma_f32_16x16x32_bf16 v[120:123], v[176:179], v[192:195], v[120:123]
	v_mfma_f32_16x16x32_bf16 v[108:111], v[168:171], v[200:203], v[108:111]
	v_mfma_f32_16x16x32_bf16 v[104:107], v[176:179], v[200:203], v[104:107]
	v_mfma_f32_16x16x32_bf16 v[68:71], v[168:171], v[228:231], v[68:71]
	v_mfma_f32_16x16x32_bf16 v[64:67], v[176:179], v[228:231], v[64:67]
	v_mfma_f32_16x16x32_bf16 v[140:143], v[172:175], v[188:191], v[140:143]
	v_mfma_f32_16x16x32_bf16 v[136:139], v[180:183], v[188:191], v[136:139]
	v_mfma_f32_16x16x32_bf16 v[124:127], v[172:175], v[196:199], v[124:127]
	v_mfma_f32_16x16x32_bf16 v[120:123], v[180:183], v[196:199], v[120:123]
	v_mfma_f32_16x16x32_bf16 v[108:111], v[172:175], v[204:207], v[108:111]
	v_mfma_f32_16x16x32_bf16 v[104:107], v[180:183], v[204:207], v[104:107]
	v_mfma_f32_16x16x32_bf16 v[68:71], v[172:175], v[240:243], v[68:71]
	v_mfma_f32_16x16x32_bf16 v[64:67], v[180:183], v[240:243], v[64:67]
	s_barrier
	ds_read_b128 v[184:187], v227 offset:49152
	ds_read_b128 v[188:191], v227 offset:50176
	ds_read_b128 v[192:195], v227 offset:51200
	ds_read_b128 v[196:199], v227 offset:52224
	ds_read_b128 v[200:203], v227 offset:53248
	ds_read_b128 v[204:207], v227 offset:54272
	ds_read_b128 v[228:231], v227 offset:55296
	ds_read_b128 v[240:243], v227 offset:56320
	s_or_b32 s36, s95, 0x4000
	s_mov_b32 m0, s77
	s_nop 0
	buffer_load_dwordx4 v224, s[48:51], s36 offen lds
	s_nop 7
	s_mov_b32 m0, s78
	s_nop 0
	buffer_load_dwordx4 v225, s[48:51], s36 offen lds
	s_add_i32 s36, s95, 0x84000
	s_mov_b32 m0, s83
	s_nop 0
	buffer_load_dwordx4 v224, s[48:51], s36 offen lds
	s_nop 7
	s_mov_b32 m0, s84
	s_nop 0
	buffer_load_dwordx4 v225, s[48:51], s36 offen lds
	s_nop 7
	s_mov_b32 m0, s79
	s_nop 0
	buffer_load_dwordx4 v224, s[60:63], s94 offen lds
	s_nop 7
	s_mov_b32 m0, s82
	s_nop 0
	buffer_load_dwordx4 v225, s[60:63], s94 offen lds
	s_waitcnt vmcnt(8)
	s_waitcnt lgkmcnt(0)
	s_barrier
	s_waitcnt lgkmcnt(7)
	v_mfma_f32_16x16x32_bf16 v[60:63], v[152:155], v[184:187], v[60:63]
	v_mfma_f32_16x16x32_bf16 v[56:59], v[160:163], v[184:187], v[56:59]
	s_waitcnt lgkmcnt(5)
	v_mfma_f32_16x16x32_bf16 v[44:47], v[152:155], v[192:195], v[44:47]
	v_mfma_f32_16x16x32_bf16 v[40:43], v[160:163], v[192:195], v[40:43]
	s_waitcnt lgkmcnt(3)
	v_mfma_f32_16x16x32_bf16 v[28:31], v[152:155], v[200:203], v[28:31]
	v_mfma_f32_16x16x32_bf16 v[24:27], v[160:163], v[200:203], v[24:27]
	s_waitcnt lgkmcnt(1)
	v_mfma_f32_16x16x32_bf16 v[12:15], v[152:155], v[228:231], v[12:15]
	v_mfma_f32_16x16x32_bf16 v[8:11], v[160:163], v[228:231], v[8:11]
	v_mfma_f32_16x16x32_bf16 v[60:63], v[156:159], v[188:191], v[60:63]
	v_mfma_f32_16x16x32_bf16 v[56:59], v[164:167], v[188:191], v[56:59]
	v_mfma_f32_16x16x32_bf16 v[44:47], v[156:159], v[196:199], v[44:47]
	v_mfma_f32_16x16x32_bf16 v[40:43], v[164:167], v[196:199], v[40:43]
	v_mfma_f32_16x16x32_bf16 v[28:31], v[156:159], v[204:207], v[28:31]
	v_mfma_f32_16x16x32_bf16 v[24:27], v[164:167], v[204:207], v[24:27]
	s_waitcnt lgkmcnt(0)
	v_mfma_f32_16x16x32_bf16 v[12:15], v[156:159], v[240:243], v[12:15]
	v_mfma_f32_16x16x32_bf16 v[8:11], v[164:167], v[240:243], v[8:11]
	v_mfma_f32_16x16x32_bf16 v[52:55], v[168:171], v[184:187], v[52:55]
	v_mfma_f32_16x16x32_bf16 v[48:51], v[176:179], v[184:187], v[48:51]
	v_mfma_f32_16x16x32_bf16 v[36:39], v[168:171], v[192:195], v[36:39]
	v_mfma_f32_16x16x32_bf16 v[32:35], v[176:179], v[192:195], v[32:35]
	v_mfma_f32_16x16x32_bf16 v[20:23], v[168:171], v[200:203], v[20:23]
	v_mfma_f32_16x16x32_bf16 v[16:19], v[176:179], v[200:203], v[16:19]
	v_mfma_f32_16x16x32_bf16 v[4:7], v[168:171], v[228:231], v[4:7]
	v_mfma_f32_16x16x32_bf16 v[0:3], v[176:179], v[228:231], v[0:3]
	v_mfma_f32_16x16x32_bf16 v[52:55], v[172:175], v[188:191], v[52:55]
	v_mfma_f32_16x16x32_bf16 v[48:51], v[180:183], v[188:191], v[48:51]
	v_mfma_f32_16x16x32_bf16 v[36:39], v[172:175], v[196:199], v[36:39]
	v_mfma_f32_16x16x32_bf16 v[32:35], v[180:183], v[196:199], v[32:35]
	v_mfma_f32_16x16x32_bf16 v[20:23], v[172:175], v[204:207], v[20:23]
	v_mfma_f32_16x16x32_bf16 v[16:19], v[180:183], v[204:207], v[16:19]
	v_mfma_f32_16x16x32_bf16 v[4:7], v[172:175], v[240:243], v[4:7]
	v_mfma_f32_16x16x32_bf16 v[0:3], v[180:183], v[240:243], v[0:3]
	s_barrier
	s_add_i32 s38, s38, 2
	s_add_i32 s39, s39, 0x8000
	s_cmp_gt_u32 s38, 29
	s_cbranch_scc1 .LBB0_597

.Lnb_p4:
	s_add_i32 s11, s8, 0xfff84000
	s_cmp_eq_u32 s10, 28
	s_cselect_b32 s13, s6, s11
	s_cselect_b32 s12, s7, s9
	s_or_b32 s11, s13, 0x4000
	s_mov_b32 m0, s89
	s_nop 0
	buffer_load_dwordx4 v220, s[64:67], s8 offen lds
	s_nop 7
	s_mov_b32 m0, s91
	s_nop 0
	buffer_load_dwordx4 v221, s[64:67], s8 offen lds
	s_waitcnt vmcnt(24)
	s_waitcnt lgkmcnt(0)
	s_barrier
	s_waitcnt lgkmcnt(7)
	v_mfma_f32_16x16x32_bf16 v[164:167], v[128:131], v[184:187], 0
	v_mfma_f32_16x16x32_bf16 v[160:163], v[152:155], v[184:187], 0
	s_waitcnt lgkmcnt(5)
	v_mfma_f32_16x16x32_bf16 v[136:139], v[128:131], v[192:195], 0
	v_mfma_f32_16x16x32_bf16 v[132:135], v[152:155], v[192:195], 0
	s_waitcnt lgkmcnt(3)
	v_mfma_f32_16x16x32_bf16 v[116:119], v[128:131], v[200:203], 0
	v_mfma_f32_16x16x32_bf16 v[112:115], v[152:155], v[200:203], 0
	s_waitcnt lgkmcnt(1)
	v_mfma_f32_16x16x32_bf16 v[76:79], v[128:131], v[224:227], 0
	v_mfma_f32_16x16x32_bf16 v[72:75], v[152:155], v[224:227], 0
	v_mfma_f32_16x16x32_bf16 v[164:167], v[140:143], v[188:191], v[164:167]
	v_mfma_f32_16x16x32_bf16 v[160:163], v[156:159], v[188:191], v[160:163]
	v_mfma_f32_16x16x32_bf16 v[136:139], v[140:143], v[196:199], v[136:139]
	v_mfma_f32_16x16x32_bf16 v[132:135], v[156:159], v[196:199], v[132:135]
	v_mfma_f32_16x16x32_bf16 v[116:119], v[140:143], v[204:207], v[116:119]
	v_mfma_f32_16x16x32_bf16 v[112:115], v[156:159], v[204:207], v[112:115]
	s_waitcnt lgkmcnt(0)
	v_mfma_f32_16x16x32_bf16 v[76:79], v[140:143], v[228:231], v[76:79]
	v_mfma_f32_16x16x32_bf16 v[72:75], v[156:159], v[228:231], v[72:75]
	v_mfma_f32_16x16x32_bf16 v[148:151], v[168:171], v[184:187], 0
	v_mfma_f32_16x16x32_bf16 v[144:147], v[176:179], v[184:187], 0
	v_mfma_f32_16x16x32_bf16 v[124:127], v[168:171], v[192:195], 0
	v_mfma_f32_16x16x32_bf16 v[120:123], v[176:179], v[192:195], 0
	v_mfma_f32_16x16x32_bf16 v[108:111], v[168:171], v[200:203], 0
	v_mfma_f32_16x16x32_bf16 v[104:107], v[176:179], v[200:203], 0
	v_mfma_f32_16x16x32_bf16 v[68:71], v[168:171], v[224:227], 0
	v_mfma_f32_16x16x32_bf16 v[64:67], v[176:179], v[224:227], 0
	v_mfma_f32_16x16x32_bf16 v[148:151], v[172:175], v[188:191], v[148:151]
	v_mfma_f32_16x16x32_bf16 v[144:147], v[180:183], v[188:191], v[144:147]
	v_mfma_f32_16x16x32_bf16 v[124:127], v[172:175], v[196:199], v[124:127]
	v_mfma_f32_16x16x32_bf16 v[120:123], v[180:183], v[196:199], v[120:123]
	v_mfma_f32_16x16x32_bf16 v[108:111], v[172:175], v[204:207], v[108:111]
	v_mfma_f32_16x16x32_bf16 v[104:107], v[180:183], v[204:207], v[104:107]
	v_mfma_f32_16x16x32_bf16 v[68:71], v[172:175], v[228:231], v[68:71]
	v_mfma_f32_16x16x32_bf16 v[64:67], v[180:183], v[228:231], v[64:67]
	s_barrier
	ds_read_b128 v[184:187], v223 offset:16384
	ds_read_b128 v[188:191], v223 offset:17408
	ds_read_b128 v[192:195], v223 offset:18432
	ds_read_b128 v[196:199], v223 offset:19456
	ds_read_b128 v[200:203], v223 offset:20480
	ds_read_b128 v[204:207], v223 offset:21504
	ds_read_b128 v[224:227], v223 offset:22528
	ds_read_b128 v[228:231], v223 offset:23552
	s_mov_b32 m0, s55
	s_nop 0
	buffer_load_dwordx4 v220, s[48:51], s12 offen lds
	s_add_i32 s14, s12, 0x80000
	s_mov_b32 m0, s76
	s_nop 0
	buffer_load_dwordx4 v221, s[48:51], s12 offen lds
	s_nop 7
	s_mov_b32 m0, s77
	s_nop 0
	buffer_load_dwordx4 v220, s[48:51], s14 offen lds
	s_nop 7
	s_mov_b32 m0, s78
	s_nop 0
	buffer_load_dwordx4 v221, s[48:51], s14 offen lds
	s_nop 7
	s_mov_b32 m0, s31
	s_nop 0
	buffer_load_dwordx4 v220, s[64:67], s13 offen lds
	s_nop 7
	s_mov_b32 m0, s79
	s_nop 0
	buffer_load_dwordx4 v221, s[64:67], s13 offen lds
	s_waitcnt vmcnt(24)
	s_waitcnt lgkmcnt(0)
	s_barrier
	s_waitcnt lgkmcnt(7)
	v_mfma_f32_16x16x32_bf16 v[60:63], v[128:131], v[184:187], 0
	v_mfma_f32_16x16x32_bf16 v[56:59], v[152:155], v[184:187], 0
	s_waitcnt lgkmcnt(5)
	v_mfma_f32_16x16x32_bf16 v[44:47], v[128:131], v[192:195], 0
	v_mfma_f32_16x16x32_bf16 v[40:43], v[152:155], v[192:195], 0
	s_waitcnt lgkmcnt(3)
	v_mfma_f32_16x16x32_bf16 v[28:31], v[128:131], v[200:203], 0
	v_mfma_f32_16x16x32_bf16 v[24:27], v[152:155], v[200:203], 0
	s_waitcnt lgkmcnt(1)
	v_mfma_f32_16x16x32_bf16 v[12:15], v[128:131], v[224:227], 0
	v_mfma_f32_16x16x32_bf16 v[8:11], v[152:155], v[224:227], 0
	v_mfma_f32_16x16x32_bf16 v[60:63], v[140:143], v[188:191], v[60:63]
	v_mfma_f32_16x16x32_bf16 v[56:59], v[156:159], v[188:191], v[56:59]
	v_mfma_f32_16x16x32_bf16 v[44:47], v[140:143], v[196:199], v[44:47]
	v_mfma_f32_16x16x32_bf16 v[40:43], v[156:159], v[196:199], v[40:43]
	v_mfma_f32_16x16x32_bf16 v[28:31], v[140:143], v[204:207], v[28:31]
	v_mfma_f32_16x16x32_bf16 v[24:27], v[156:159], v[204:207], v[24:27]
	s_waitcnt lgkmcnt(0)
	v_mfma_f32_16x16x32_bf16 v[12:15], v[140:143], v[228:231], v[12:15]
	v_mfma_f32_16x16x32_bf16 v[8:11], v[156:159], v[228:231], v[8:11]
	v_mfma_f32_16x16x32_bf16 v[52:55], v[168:171], v[184:187], 0
	v_mfma_f32_16x16x32_bf16 v[48:51], v[176:179], v[184:187], 0
	v_mfma_f32_16x16x32_bf16 v[36:39], v[168:171], v[192:195], 0
	v_mfma_f32_16x16x32_bf16 v[32:35], v[176:179], v[192:195], 0
	v_mfma_f32_16x16x32_bf16 v[20:23], v[168:171], v[200:203], 0
	v_mfma_f32_16x16x32_bf16 v[16:19], v[176:179], v[200:203], 0
	v_mfma_f32_16x16x32_bf16 v[4:7], v[168:171], v[224:227], 0
	v_mfma_f32_16x16x32_bf16 v[0:3], v[176:179], v[224:227], 0
	v_mfma_f32_16x16x32_bf16 v[52:55], v[172:175], v[188:191], v[52:55]
	v_mfma_f32_16x16x32_bf16 v[48:51], v[180:183], v[188:191], v[48:51]
	v_mfma_f32_16x16x32_bf16 v[36:39], v[172:175], v[196:199], v[36:39]
	v_mfma_f32_16x16x32_bf16 v[32:35], v[180:183], v[196:199], v[32:35]
	v_mfma_f32_16x16x32_bf16 v[20:23], v[172:175], v[204:207], v[20:23]
	v_mfma_f32_16x16x32_bf16 v[16:19], v[180:183], v[204:207], v[16:19]
	v_mfma_f32_16x16x32_bf16 v[4:7], v[172:175], v[228:231], v[4:7]
	v_mfma_f32_16x16x32_bf16 v[0:3], v[180:183], v[228:231], v[0:3]
	s_barrier
	v_add_u32_e32 v156, 0x18000, v222
	v_add_u32_e32 v180, 0x1c000, v222
	ds_read_b128 v[128:131], v156
	ds_read_b128 v[140:143], v156 offset:1024
	ds_read_b128 v[152:155], v156 offset:2048
	ds_read_b128 v[156:159], v156 offset:3072
	ds_read_b128 v[168:171], v180
	ds_read_b128 v[172:175], v180 offset:1024
	ds_read_b128 v[176:179], v180 offset:2048
	ds_read_b128 v[180:183], v180 offset:3072
	ds_read_b128 v[184:187], v223 offset:32768
	ds_read_b128 v[188:191], v223 offset:33792
	ds_read_b128 v[192:195], v223 offset:34816
	ds_read_b128 v[196:199], v223 offset:35840
	ds_read_b128 v[200:203], v223 offset:36864
	ds_read_b128 v[204:207], v223 offset:37888
	ds_read_b128 v[224:227], v223 offset:38912
	ds_read_b128 v[228:231], v223 offset:39936
	s_add_i32 s13, s13, 0x80000
	s_mov_b32 m0, s82
	s_nop 0
	buffer_load_dwordx4 v220, s[64:67], s13 offen lds
	s_nop 7
	s_mov_b32 m0, s83
	s_nop 0
	buffer_load_dwordx4 v221, s[64:67], s13 offen lds
	s_waitcnt vmcnt(8)
	s_waitcnt lgkmcnt(0)
	s_barrier
	s_waitcnt lgkmcnt(7)
	v_mfma_f32_16x16x32_bf16 v[164:167], v[128:131], v[184:187], v[164:167]
	v_mfma_f32_16x16x32_bf16 v[160:163], v[152:155], v[184:187], v[160:163]
	s_waitcnt lgkmcnt(5)
	v_mfma_f32_16x16x32_bf16 v[136:139], v[128:131], v[192:195], v[136:139]
	v_mfma_f32_16x16x32_bf16 v[132:135], v[152:155], v[192:195], v[132:135]
	s_waitcnt lgkmcnt(3)
	v_mfma_f32_16x16x32_bf16 v[116:119], v[128:131], v[200:203], v[116:119]
	v_mfma_f32_16x16x32_bf16 v[112:115], v[152:155], v[200:203], v[112:115]
	s_waitcnt lgkmcnt(1)
	v_mfma_f32_16x16x32_bf16 v[76:79], v[128:131], v[224:227], v[76:79]
	v_mfma_f32_16x16x32_bf16 v[72:75], v[152:155], v[224:227], v[72:75]
	v_mfma_f32_16x16x32_bf16 v[164:167], v[140:143], v[188:191], v[164:167]
	v_mfma_f32_16x16x32_bf16 v[160:163], v[156:159], v[188:191], v[160:163]
	v_mfma_f32_16x16x32_bf16 v[136:139], v[140:143], v[196:199], v[136:139]
	v_mfma_f32_16x16x32_bf16 v[132:135], v[156:159], v[196:199], v[132:135]
	v_mfma_f32_16x16x32_bf16 v[116:119], v[140:143], v[204:207], v[116:119]
	v_mfma_f32_16x16x32_bf16 v[112:115], v[156:159], v[204:207], v[112:115]
	s_waitcnt lgkmcnt(0)
	v_mfma_f32_16x16x32_bf16 v[76:79], v[140:143], v[228:231], v[76:79]
	v_mfma_f32_16x16x32_bf16 v[72:75], v[156:159], v[228:231], v[72:75]
	v_mfma_f32_16x16x32_bf16 v[148:151], v[168:171], v[184:187], v[148:151]
	v_mfma_f32_16x16x32_bf16 v[144:147], v[176:179], v[184:187], v[144:147]
	v_mfma_f32_16x16x32_bf16 v[124:127], v[168:171], v[192:195], v[124:127]
	v_mfma_f32_16x16x32_bf16 v[120:123], v[176:179], v[192:195], v[120:123]
	v_mfma_f32_16x16x32_bf16 v[108:111], v[168:171], v[200:203], v[108:111]
	v_mfma_f32_16x16x32_bf16 v[104:107], v[176:179], v[200:203], v[104:107]
	v_mfma_f32_16x16x32_bf16 v[68:71], v[168:171], v[224:227], v[68:71]
	v_mfma_f32_16x16x32_bf16 v[64:67], v[176:179], v[224:227], v[64:67]
	v_mfma_f32_16x16x32_bf16 v[148:151], v[172:175], v[188:191], v[148:151]
	v_mfma_f32_16x16x32_bf16 v[144:147], v[180:183], v[188:191], v[144:147]
	v_mfma_f32_16x16x32_bf16 v[124:127], v[172:175], v[196:199], v[124:127]
	v_mfma_f32_16x16x32_bf16 v[120:123], v[180:183], v[196:199], v[120:123]
	v_mfma_f32_16x16x32_bf16 v[108:111], v[172:175], v[204:207], v[108:111]
	v_mfma_f32_16x16x32_bf16 v[104:107], v[180:183], v[204:207], v[104:107]
	v_mfma_f32_16x16x32_bf16 v[68:71], v[172:175], v[228:231], v[68:71]
	v_mfma_f32_16x16x32_bf16 v[64:67], v[180:183], v[228:231], v[64:67]
	s_barrier
	ds_read_b128 v[184:187], v223 offset:49152
	ds_read_b128 v[188:191], v223 offset:50176
	ds_read_b128 v[192:195], v223 offset:51200
	ds_read_b128 v[196:199], v223 offset:52224
	ds_read_b128 v[200:203], v223 offset:53248
	ds_read_b128 v[204:207], v223 offset:54272
	ds_read_b128 v[224:227], v223 offset:55296
	ds_read_b128 v[228:231], v223 offset:56320
	s_or_b32 s13, s12, 0x4000
	s_mov_b32 m0, s34
	s_nop 0
	buffer_load_dwordx4 v220, s[48:51], s13 offen lds
	s_add_i32 s12, s12, 0x84000
	s_mov_b32 m0, s84
	s_nop 0
	buffer_load_dwordx4 v221, s[48:51], s13 offen lds
	s_nop 7
	s_mov_b32 m0, s87
	s_nop 0
	buffer_load_dwordx4 v220, s[48:51], s12 offen lds
	s_nop 7
	s_mov_b32 m0, s88
	s_nop 0
	buffer_load_dwordx4 v221, s[48:51], s12 offen lds
	s_nop 7
	s_mov_b32 m0, s85
	s_nop 0
	buffer_load_dwordx4 v220, s[64:67], s11 offen lds
	s_nop 7
	s_mov_b32 m0, s86
	s_nop 0
	buffer_load_dwordx4 v221, s[64:67], s11 offen lds
	s_waitcnt vmcnt(8)
	s_waitcnt lgkmcnt(0)
	s_barrier
	s_waitcnt lgkmcnt(7)
	v_mfma_f32_16x16x32_bf16 v[60:63], v[128:131], v[184:187], v[60:63]
	v_mfma_f32_16x16x32_bf16 v[56:59], v[152:155], v[184:187], v[56:59]
	s_waitcnt lgkmcnt(5)
	v_mfma_f32_16x16x32_bf16 v[44:47], v[128:131], v[192:195], v[44:47]
	v_mfma_f32_16x16x32_bf16 v[40:43], v[152:155], v[192:195], v[40:43]
	s_waitcnt lgkmcnt(3)
	v_mfma_f32_16x16x32_bf16 v[28:31], v[128:131], v[200:203], v[28:31]
	v_mfma_f32_16x16x32_bf16 v[24:27], v[152:155], v[200:203], v[24:27]
	s_waitcnt lgkmcnt(1)
	v_mfma_f32_16x16x32_bf16 v[12:15], v[128:131], v[224:227], v[12:15]
	v_mfma_f32_16x16x32_bf16 v[8:11], v[152:155], v[224:227], v[8:11]
	v_mfma_f32_16x16x32_bf16 v[60:63], v[140:143], v[188:191], v[60:63]
	v_mfma_f32_16x16x32_bf16 v[56:59], v[156:159], v[188:191], v[56:59]
	v_mfma_f32_16x16x32_bf16 v[44:47], v[140:143], v[196:199], v[44:47]
	v_mfma_f32_16x16x32_bf16 v[40:43], v[156:159], v[196:199], v[40:43]
	v_mfma_f32_16x16x32_bf16 v[28:31], v[140:143], v[204:207], v[28:31]
	v_mfma_f32_16x16x32_bf16 v[24:27], v[156:159], v[204:207], v[24:27]
	s_waitcnt lgkmcnt(0)
	v_mfma_f32_16x16x32_bf16 v[12:15], v[140:143], v[228:231], v[12:15]
	v_mfma_f32_16x16x32_bf16 v[8:11], v[156:159], v[228:231], v[8:11]
	v_mfma_f32_16x16x32_bf16 v[52:55], v[168:171], v[184:187], v[52:55]
	v_mfma_f32_16x16x32_bf16 v[48:51], v[176:179], v[184:187], v[48:51]
	v_mfma_f32_16x16x32_bf16 v[36:39], v[168:171], v[192:195], v[36:39]
	v_mfma_f32_16x16x32_bf16 v[32:35], v[176:179], v[192:195], v[32:35]
	v_mfma_f32_16x16x32_bf16 v[20:23], v[168:171], v[200:203], v[20:23]
	v_mfma_f32_16x16x32_bf16 v[16:19], v[176:179], v[200:203], v[16:19]
	v_mfma_f32_16x16x32_bf16 v[4:7], v[168:171], v[224:227], v[4:7]
	v_mfma_f32_16x16x32_bf16 v[0:3], v[176:179], v[224:227], v[0:3]
	v_mfma_f32_16x16x32_bf16 v[52:55], v[172:175], v[188:191], v[52:55]
	v_mfma_f32_16x16x32_bf16 v[48:51], v[180:183], v[188:191], v[48:51]
	v_mfma_f32_16x16x32_bf16 v[36:39], v[172:175], v[196:199], v[36:39]
	v_mfma_f32_16x16x32_bf16 v[32:35], v[180:183], v[196:199], v[32:35]
	v_mfma_f32_16x16x32_bf16 v[20:23], v[172:175], v[204:207], v[20:23]
	v_mfma_f32_16x16x32_bf16 v[16:19], v[180:183], v[204:207], v[16:19]
	v_mfma_f32_16x16x32_bf16 v[4:7], v[172:175], v[228:231], v[4:7]
	v_mfma_f32_16x16x32_bf16 v[0:3], v[180:183], v[228:231], v[0:3]
	s_barrier
	s_add_i32 s10, s10, 2
	s_add_i32 s8, s8, 0x8000
	s_add_i32 s9, s9, 0x8000
.LBB0_691:
	v_add_u32_e32 v156, 0x10000, v222
	v_add_u32_e32 v180, 0x14000, v222
	ds_read_b128 v[128:131], v156
	ds_read_b128 v[140:143], v156 offset:1024
	ds_read_b128 v[152:155], v156 offset:2048
	ds_read_b128 v[156:159], v156 offset:3072
	ds_read_b128 v[168:171], v180
	ds_read_b128 v[172:175], v180 offset:1024
	ds_read_b128 v[176:179], v180 offset:2048
	ds_read_b128 v[180:183], v180 offset:3072
	s_add_i32 s11, s8, 0xfff84000
	s_cmp_eq_u32 s10, 28
	s_cselect_b32 s13, s6, s11
	s_cselect_b32 s12, s7, s9
	s_or_b32 s11, s13, 0x4000
	ds_read_b128 v[184:187], v223
	ds_read_b128 v[188:191], v223 offset:1024
	ds_read_b128 v[192:195], v223 offset:2048
	ds_read_b128 v[196:199], v223 offset:3072
	ds_read_b128 v[200:203], v223 offset:4096
	ds_read_b128 v[204:207], v223 offset:5120
	ds_read_b128 v[224:227], v223 offset:6144
	ds_read_b128 v[228:231], v223 offset:7168
	s_mov_b32 m0, s89
	s_nop 0
	buffer_load_dwordx4 v220, s[64:67], s8 offen lds
	s_nop 7
	s_mov_b32 m0, s91
	s_nop 0
	buffer_load_dwordx4 v221, s[64:67], s8 offen lds
	s_waitcnt vmcnt(8)
	s_waitcnt lgkmcnt(0)
	s_barrier
	s_waitcnt lgkmcnt(7)
	v_mfma_f32_16x16x32_bf16 v[164:167], v[128:131], v[184:187], v[164:167]
	v_mfma_f32_16x16x32_bf16 v[160:163], v[152:155], v[184:187], v[160:163]
	s_waitcnt lgkmcnt(5)
	v_mfma_f32_16x16x32_bf16 v[136:139], v[128:131], v[192:195], v[136:139]
	v_mfma_f32_16x16x32_bf16 v[132:135], v[152:155], v[192:195], v[132:135]
	s_waitcnt lgkmcnt(3)
	v_mfma_f32_16x16x32_bf16 v[116:119], v[128:131], v[200:203], v[116:119]
	v_mfma_f32_16x16x32_bf16 v[112:115], v[152:155], v[200:203], v[112:115]
	s_waitcnt lgkmcnt(1)
	v_mfma_f32_16x16x32_bf16 v[76:79], v[128:131], v[224:227], v[76:79]
	v_mfma_f32_16x16x32_bf16 v[72:75], v[152:155], v[224:227], v[72:75]
	v_mfma_f32_16x16x32_bf16 v[164:167], v[140:143], v[188:191], v[164:167]
	v_mfma_f32_16x16x32_bf16 v[160:163], v[156:159], v[188:191], v[160:163]
	v_mfma_f32_16x16x32_bf16 v[136:139], v[140:143], v[196:199], v[136:139]
	v_mfma_f32_16x16x32_bf16 v[132:135], v[156:159], v[196:199], v[132:135]
	v_mfma_f32_16x16x32_bf16 v[116:119], v[140:143], v[204:207], v[116:119]
	v_mfma_f32_16x16x32_bf16 v[112:115], v[156:159], v[204:207], v[112:115]
	s_waitcnt lgkmcnt(0)
	v_mfma_f32_16x16x32_bf16 v[76:79], v[140:143], v[228:231], v[76:79]
	v_mfma_f32_16x16x32_bf16 v[72:75], v[156:159], v[228:231], v[72:75]
	v_mfma_f32_16x16x32_bf16 v[148:151], v[168:171], v[184:187], v[148:151]
	v_mfma_f32_16x16x32_bf16 v[144:147], v[176:179], v[184:187], v[144:147]
	v_mfma_f32_16x16x32_bf16 v[124:127], v[168:171], v[192:195], v[124:127]
	v_mfma_f32_16x16x32_bf16 v[120:123], v[176:179], v[192:195], v[120:123]
	v_mfma_f32_16x16x32_bf16 v[108:111], v[168:171], v[200:203], v[108:111]
	v_mfma_f32_16x16x32_bf16 v[104:107], v[176:179], v[200:203], v[104:107]
	v_mfma_f32_16x16x32_bf16 v[68:71], v[168:171], v[224:227], v[68:71]
	v_mfma_f32_16x16x32_bf16 v[64:67], v[176:179], v[224:227], v[64:67]
	v_mfma_f32_16x16x32_bf16 v[148:151], v[172:175], v[188:191], v[148:151]
	v_mfma_f32_16x16x32_bf16 v[144:147], v[180:183], v[188:191], v[144:147]
	v_mfma_f32_16x16x32_bf16 v[124:127], v[172:175], v[196:199], v[124:127]
	v_mfma_f32_16x16x32_bf16 v[120:123], v[180:183], v[196:199], v[120:123]
	v_mfma_f32_16x16x32_bf16 v[108:111], v[172:175], v[204:207], v[108:111]
	v_mfma_f32_16x16x32_bf16 v[104:107], v[180:183], v[204:207], v[104:107]
	v_mfma_f32_16x16x32_bf16 v[68:71], v[172:175], v[228:231], v[68:71]
	v_mfma_f32_16x16x32_bf16 v[64:67], v[180:183], v[228:231], v[64:67]
	s_barrier
	ds_read_b128 v[184:187], v223 offset:16384
	ds_read_b128 v[188:191], v223 offset:17408
	ds_read_b128 v[192:195], v223 offset:18432
	ds_read_b128 v[196:199], v223 offset:19456
	ds_read_b128 v[200:203], v223 offset:20480
	ds_read_b128 v[204:207], v223 offset:21504
	ds_read_b128 v[224:227], v223 offset:22528
	ds_read_b128 v[228:231], v223 offset:23552
	s_mov_b32 m0, s55
	s_nop 0
	buffer_load_dwordx4 v220, s[48:51], s12 offen lds
	s_add_i32 s14, s12, 0x80000
	s_mov_b32 m0, s76
	s_nop 0
	buffer_load_dwordx4 v221, s[48:51], s12 offen lds
	s_nop 7
	s_mov_b32 m0, s77
	s_nop 0
	buffer_load_dwordx4 v220, s[48:51], s14 offen lds
	s_nop 7
	s_mov_b32 m0, s78
	s_nop 0
	buffer_load_dwordx4 v221, s[48:51], s14 offen lds
	s_nop 7
	s_mov_b32 m0, s31
	s_nop 0
	buffer_load_dwordx4 v220, s[64:67], s13 offen lds
	s_nop 7
	s_mov_b32 m0, s79
	s_nop 0
	buffer_load_dwordx4 v221, s[64:67], s13 offen lds
	s_waitcnt vmcnt(8)
	s_waitcnt lgkmcnt(0)
	s_barrier
	s_waitcnt lgkmcnt(7)
	v_mfma_f32_16x16x32_bf16 v[60:63], v[128:131], v[184:187], v[60:63]
	v_mfma_f32_16x16x32_bf16 v[56:59], v[152:155], v[184:187], v[56:59]
	s_waitcnt lgkmcnt(5)
	v_mfma_f32_16x16x32_bf16 v[44:47], v[128:131], v[192:195], v[44:47]
	v_mfma_f32_16x16x32_bf16 v[40:43], v[152:155], v[192:195], v[40:43]
	s_waitcnt lgkmcnt(3)
	v_mfma_f32_16x16x32_bf16 v[28:31], v[128:131], v[200:203], v[28:31]
	v_mfma_f32_16x16x32_bf16 v[24:27], v[152:155], v[200:203], v[24:27]
	s_waitcnt lgkmcnt(1)
	v_mfma_f32_16x16x32_bf16 v[12:15], v[128:131], v[224:227], v[12:15]
	v_mfma_f32_16x16x32_bf16 v[8:11], v[152:155], v[224:227], v[8:11]
	v_mfma_f32_16x16x32_bf16 v[60:63], v[140:143], v[188:191], v[60:63]
	v_mfma_f32_16x16x32_bf16 v[56:59], v[156:159], v[188:191], v[56:59]
	v_mfma_f32_16x16x32_bf16 v[44:47], v[140:143], v[196:199], v[44:47]
	v_mfma_f32_16x16x32_bf16 v[40:43], v[156:159], v[196:199], v[40:43]
	v_mfma_f32_16x16x32_bf16 v[28:31], v[140:143], v[204:207], v[28:31]
	v_mfma_f32_16x16x32_bf16 v[24:27], v[156:159], v[204:207], v[24:27]
	s_waitcnt lgkmcnt(0)
	v_mfma_f32_16x16x32_bf16 v[12:15], v[140:143], v[228:231], v[12:15]
	v_mfma_f32_16x16x32_bf16 v[8:11], v[156:159], v[228:231], v[8:11]
	v_mfma_f32_16x16x32_bf16 v[52:55], v[168:171], v[184:187], v[52:55]
	v_mfma_f32_16x16x32_bf16 v[48:51], v[176:179], v[184:187], v[48:51]
	v_mfma_f32_16x16x32_bf16 v[36:39], v[168:171], v[192:195], v[36:39]
	v_mfma_f32_16x16x32_bf16 v[32:35], v[176:179], v[192:195], v[32:35]
	v_mfma_f32_16x16x32_bf16 v[20:23], v[168:171], v[200:203], v[20:23]
	v_mfma_f32_16x16x32_bf16 v[16:19], v[176:179], v[200:203], v[16:19]
	v_mfma_f32_16x16x32_bf16 v[4:7], v[168:171], v[224:227], v[4:7]
	v_mfma_f32_16x16x32_bf16 v[0:3], v[176:179], v[224:227], v[0:3]
	v_mfma_f32_16x16x32_bf16 v[52:55], v[172:175], v[188:191], v[52:55]
	v_mfma_f32_16x16x32_bf16 v[48:51], v[180:183], v[188:191], v[48:51]
	v_mfma_f32_16x16x32_bf16 v[36:39], v[172:175], v[196:199], v[36:39]
	v_mfma_f32_16x16x32_bf16 v[32:35], v[180:183], v[196:199], v[32:35]
	v_mfma_f32_16x16x32_bf16 v[20:23], v[172:175], v[204:207], v[20:23]
	v_mfma_f32_16x16x32_bf16 v[16:19], v[180:183], v[204:207], v[16:19]
	v_mfma_f32_16x16x32_bf16 v[4:7], v[172:175], v[228:231], v[4:7]
	v_mfma_f32_16x16x32_bf16 v[0:3], v[180:183], v[228:231], v[0:3]
	s_barrier
	v_add_u32_e32 v156, 0x18000, v222
	v_add_u32_e32 v180, 0x1c000, v222
	ds_read_b128 v[128:131], v156
	ds_read_b128 v[140:143], v156 offset:1024
	ds_read_b128 v[152:155], v156 offset:2048
	ds_read_b128 v[156:159], v156 offset:3072
	ds_read_b128 v[168:171], v180
	ds_read_b128 v[172:175], v180 offset:1024
	ds_read_b128 v[176:179], v180 offset:2048
	ds_read_b128 v[180:183], v180 offset:3072
	ds_read_b128 v[184:187], v223 offset:32768
	ds_read_b128 v[188:191], v223 offset:33792
	ds_read_b128 v[192:195], v223 offset:34816
	ds_read_b128 v[196:199], v223 offset:35840
	ds_read_b128 v[200:203], v223 offset:36864
	ds_read_b128 v[204:207], v223 offset:37888
	ds_read_b128 v[224:227], v223 offset:38912
	ds_read_b128 v[228:231], v223 offset:39936
	s_add_i32 s13, s13, 0x80000
	s_mov_b32 m0, s82
	s_nop 0
	buffer_load_dwordx4 v220, s[64:67], s13 offen lds
	s_nop 7
	s_mov_b32 m0, s83
	s_nop 0
	buffer_load_dwordx4 v221, s[64:67], s13 offen lds
	s_waitcnt vmcnt(8)
	s_waitcnt lgkmcnt(0)
	s_barrier
	s_waitcnt lgkmcnt(7)
	v_mfma_f32_16x16x32_bf16 v[164:167], v[128:131], v[184:187], v[164:167]
	v_mfma_f32_16x16x32_bf16 v[160:163], v[152:155], v[184:187], v[160:163]
	s_waitcnt lgkmcnt(5)
	v_mfma_f32_16x16x32_bf16 v[136:139], v[128:131], v[192:195], v[136:139]
	v_mfma_f32_16x16x32_bf16 v[132:135], v[152:155], v[192:195], v[132:135]
	s_waitcnt lgkmcnt(3)
	v_mfma_f32_16x16x32_bf16 v[116:119], v[128:131], v[200:203], v[116:119]
	v_mfma_f32_16x16x32_bf16 v[112:115], v[152:155], v[200:203], v[112:115]
	s_waitcnt lgkmcnt(1)
	v_mfma_f32_16x16x32_bf16 v[76:79], v[128:131], v[224:227], v[76:79]
	v_mfma_f32_16x16x32_bf16 v[72:75], v[152:155], v[224:227], v[72:75]
	v_mfma_f32_16x16x32_bf16 v[164:167], v[140:143], v[188:191], v[164:167]
	v_mfma_f32_16x16x32_bf16 v[160:163], v[156:159], v[188:191], v[160:163]
	v_mfma_f32_16x16x32_bf16 v[136:139], v[140:143], v[196:199], v[136:139]
	v_mfma_f32_16x16x32_bf16 v[132:135], v[156:159], v[196:199], v[132:135]
	v_mfma_f32_16x16x32_bf16 v[116:119], v[140:143], v[204:207], v[116:119]
	v_mfma_f32_16x16x32_bf16 v[112:115], v[156:159], v[204:207], v[112:115]
	s_waitcnt lgkmcnt(0)
	v_mfma_f32_16x16x32_bf16 v[76:79], v[140:143], v[228:231], v[76:79]
	v_mfma_f32_16x16x32_bf16 v[72:75], v[156:159], v[228:231], v[72:75]
	v_mfma_f32_16x16x32_bf16 v[148:151], v[168:171], v[184:187], v[148:151]
	v_mfma_f32_16x16x32_bf16 v[144:147], v[176:179], v[184:187], v[144:147]
	v_mfma_f32_16x16x32_bf16 v[124:127], v[168:171], v[192:195], v[124:127]
	v_mfma_f32_16x16x32_bf16 v[120:123], v[176:179], v[192:195], v[120:123]
	v_mfma_f32_16x16x32_bf16 v[108:111], v[168:171], v[200:203], v[108:111]
	v_mfma_f32_16x16x32_bf16 v[104:107], v[176:179], v[200:203], v[104:107]
	v_mfma_f32_16x16x32_bf16 v[68:71], v[168:171], v[224:227], v[68:71]
	v_mfma_f32_16x16x32_bf16 v[64:67], v[176:179], v[224:227], v[64:67]
	v_mfma_f32_16x16x32_bf16 v[148:151], v[172:175], v[188:191], v[148:151]
	v_mfma_f32_16x16x32_bf16 v[144:147], v[180:183], v[188:191], v[144:147]
	v_mfma_f32_16x16x32_bf16 v[124:127], v[172:175], v[196:199], v[124:127]
	v_mfma_f32_16x16x32_bf16 v[120:123], v[180:183], v[196:199], v[120:123]
	v_mfma_f32_16x16x32_bf16 v[108:111], v[172:175], v[204:207], v[108:111]
	v_mfma_f32_16x16x32_bf16 v[104:107], v[180:183], v[204:207], v[104:107]
	v_mfma_f32_16x16x32_bf16 v[68:71], v[172:175], v[228:231], v[68:71]
	v_mfma_f32_16x16x32_bf16 v[64:67], v[180:183], v[228:231], v[64:67]
	s_barrier
	ds_read_b128 v[184:187], v223 offset:49152
	ds_read_b128 v[188:191], v223 offset:50176
	ds_read_b128 v[192:195], v223 offset:51200
	ds_read_b128 v[196:199], v223 offset:52224
	ds_read_b128 v[200:203], v223 offset:53248
	ds_read_b128 v[204:207], v223 offset:54272
	ds_read_b128 v[224:227], v223 offset:55296
	ds_read_b128 v[228:231], v223 offset:56320
	s_or_b32 s13, s12, 0x4000
	s_mov_b32 m0, s34
	s_nop 0
	buffer_load_dwordx4 v220, s[48:51], s13 offen lds
	s_add_i32 s12, s12, 0x84000
	s_mov_b32 m0, s84
	s_nop 0
	buffer_load_dwordx4 v221, s[48:51], s13 offen lds
	s_nop 7
	s_mov_b32 m0, s87
	s_nop 0
	buffer_load_dwordx4 v220, s[48:51], s12 offen lds
	s_nop 7
	s_mov_b32 m0, s88
	s_nop 0
	buffer_load_dwordx4 v221, s[48:51], s12 offen lds
	s_nop 7
	s_mov_b32 m0, s85
	s_nop 0
	buffer_load_dwordx4 v220, s[64:67], s11 offen lds
	s_nop 7
	s_mov_b32 m0, s86
	s_nop 0
	buffer_load_dwordx4 v221, s[64:67], s11 offen lds
	s_waitcnt vmcnt(8)
	s_waitcnt lgkmcnt(0)
	s_barrier
	s_waitcnt lgkmcnt(7)
	v_mfma_f32_16x16x32_bf16 v[60:63], v[128:131], v[184:187], v[60:63]
	v_mfma_f32_16x16x32_bf16 v[56:59], v[152:155], v[184:187], v[56:59]
	s_waitcnt lgkmcnt(5)
	v_mfma_f32_16x16x32_bf16 v[44:47], v[128:131], v[192:195], v[44:47]
	v_mfma_f32_16x16x32_bf16 v[40:43], v[152:155], v[192:195], v[40:43]
	s_waitcnt lgkmcnt(3)
	v_mfma_f32_16x16x32_bf16 v[28:31], v[128:131], v[200:203], v[28:31]
	v_mfma_f32_16x16x32_bf16 v[24:27], v[152:155], v[200:203], v[24:27]
	s_waitcnt lgkmcnt(1)
	v_mfma_f32_16x16x32_bf16 v[12:15], v[128:131], v[224:227], v[12:15]
	v_mfma_f32_16x16x32_bf16 v[8:11], v[152:155], v[224:227], v[8:11]
	v_mfma_f32_16x16x32_bf16 v[60:63], v[140:143], v[188:191], v[60:63]
	v_mfma_f32_16x16x32_bf16 v[56:59], v[156:159], v[188:191], v[56:59]
	v_mfma_f32_16x16x32_bf16 v[44:47], v[140:143], v[196:199], v[44:47]
	v_mfma_f32_16x16x32_bf16 v[40:43], v[156:159], v[196:199], v[40:43]
	v_mfma_f32_16x16x32_bf16 v[28:31], v[140:143], v[204:207], v[28:31]
	v_mfma_f32_16x16x32_bf16 v[24:27], v[156:159], v[204:207], v[24:27]
	s_waitcnt lgkmcnt(0)
	v_mfma_f32_16x16x32_bf16 v[12:15], v[140:143], v[228:231], v[12:15]
	v_mfma_f32_16x16x32_bf16 v[8:11], v[156:159], v[228:231], v[8:11]
	v_mfma_f32_16x16x32_bf16 v[52:55], v[168:171], v[184:187], v[52:55]
	v_mfma_f32_16x16x32_bf16 v[48:51], v[176:179], v[184:187], v[48:51]
	v_mfma_f32_16x16x32_bf16 v[36:39], v[168:171], v[192:195], v[36:39]
	v_mfma_f32_16x16x32_bf16 v[32:35], v[176:179], v[192:195], v[32:35]
	v_mfma_f32_16x16x32_bf16 v[20:23], v[168:171], v[200:203], v[20:23]
	v_mfma_f32_16x16x32_bf16 v[16:19], v[176:179], v[200:203], v[16:19]
	v_mfma_f32_16x16x32_bf16 v[4:7], v[168:171], v[224:227], v[4:7]
	v_mfma_f32_16x16x32_bf16 v[0:3], v[176:179], v[224:227], v[0:3]
	v_mfma_f32_16x16x32_bf16 v[52:55], v[172:175], v[188:191], v[52:55]
	v_mfma_f32_16x16x32_bf16 v[48:51], v[180:183], v[188:191], v[48:51]
	v_mfma_f32_16x16x32_bf16 v[36:39], v[172:175], v[196:199], v[36:39]
	v_mfma_f32_16x16x32_bf16 v[32:35], v[180:183], v[196:199], v[32:35]
	v_mfma_f32_16x16x32_bf16 v[20:23], v[172:175], v[204:207], v[20:23]
	v_mfma_f32_16x16x32_bf16 v[16:19], v[180:183], v[204:207], v[16:19]
	v_mfma_f32_16x16x32_bf16 v[4:7], v[172:175], v[228:231], v[4:7]
	v_mfma_f32_16x16x32_bf16 v[0:3], v[180:183], v[228:231], v[0:3]
	s_barrier
	s_add_i32 s10, s10, 2
	s_add_i32 s8, s8, 0x8000
	s_add_i32 s9, s9, 0x8000
	s_cmp_gt_u32 s10, 29
	s_cbranch_scc0 .LBB0_691

.Lnb_p5:
	s_add_i32 s53, s37, 0xfff84000
	s_cmp_eq_u32 s52, 28
	s_cselect_b32 s56, s4, s53
	s_cselect_b32 s55, s5, s51
	s_or_b32 s53, s56, 0x4000
	s_mov_b32 m0, s41
	s_nop 0
	buffer_load_dwordx4 v166, s[24:27], s37 offen lds
	s_nop 7
	s_mov_b32 m0, s42
	s_nop 0
	buffer_load_dwordx4 v167, s[24:27], s37 offen lds
	s_waitcnt vmcnt(24)
	s_waitcnt lgkmcnt(0)
	s_barrier
	s_waitcnt lgkmcnt(7)
	v_mfma_f32_16x16x32_bf16 v[148:151], v[152:155], v[190:193], 0
	v_mfma_f32_16x16x32_bf16 v[140:143], v[160:163], v[190:193], 0
	s_waitcnt lgkmcnt(5)
	v_mfma_f32_16x16x32_bf16 v[132:135], v[152:155], v[198:201], 0
	v_mfma_f32_16x16x32_bf16 v[124:127], v[160:163], v[198:201], 0
	s_waitcnt lgkmcnt(3)
	v_mfma_f32_16x16x32_bf16 v[116:119], v[152:155], v[220:223], 0
	v_mfma_f32_16x16x32_bf16 v[108:111], v[160:163], v[220:223], 0
	s_waitcnt lgkmcnt(1)
	v_mfma_f32_16x16x32_bf16 v[76:79], v[152:155], v[228:231], 0
	v_mfma_f32_16x16x32_bf16 v[68:71], v[160:163], v[228:231], 0
	v_mfma_f32_16x16x32_bf16 v[148:151], v[156:159], v[194:197], v[148:151]
	v_mfma_f32_16x16x32_bf16 v[140:143], v[170:173], v[194:197], v[140:143]
	v_mfma_f32_16x16x32_bf16 v[132:135], v[156:159], v[202:205], v[132:135]
	v_mfma_f32_16x16x32_bf16 v[124:127], v[170:173], v[202:205], v[124:127]
	v_mfma_f32_16x16x32_bf16 v[116:119], v[156:159], v[224:227], v[116:119]
	v_mfma_f32_16x16x32_bf16 v[108:111], v[170:173], v[224:227], v[108:111]
	s_waitcnt lgkmcnt(0)
	v_mfma_f32_16x16x32_bf16 v[76:79], v[156:159], v[240:243], v[76:79]
	v_mfma_f32_16x16x32_bf16 v[68:71], v[170:173], v[240:243], v[68:71]
	v_mfma_f32_16x16x32_bf16 v[144:147], v[174:177], v[190:193], 0
	v_mfma_f32_16x16x32_bf16 v[136:139], v[182:185], v[190:193], 0
	v_mfma_f32_16x16x32_bf16 v[128:131], v[174:177], v[198:201], 0
	v_mfma_f32_16x16x32_bf16 v[120:123], v[182:185], v[198:201], 0
	v_mfma_f32_16x16x32_bf16 v[112:115], v[174:177], v[220:223], 0
	v_mfma_f32_16x16x32_bf16 v[104:107], v[182:185], v[220:223], 0
	v_mfma_f32_16x16x32_bf16 v[72:75], v[174:177], v[228:231], 0
	v_mfma_f32_16x16x32_bf16 v[64:67], v[182:185], v[228:231], 0
	v_mfma_f32_16x16x32_bf16 v[144:147], v[178:181], v[194:197], v[144:147]
	v_mfma_f32_16x16x32_bf16 v[136:139], v[186:189], v[194:197], v[136:139]
	v_mfma_f32_16x16x32_bf16 v[128:131], v[178:181], v[202:205], v[128:131]
	v_mfma_f32_16x16x32_bf16 v[120:123], v[186:189], v[202:205], v[120:123]
	v_mfma_f32_16x16x32_bf16 v[112:115], v[178:181], v[224:227], v[112:115]
	v_mfma_f32_16x16x32_bf16 v[104:107], v[186:189], v[224:227], v[104:107]
	v_mfma_f32_16x16x32_bf16 v[72:75], v[178:181], v[240:243], v[72:75]
	v_mfma_f32_16x16x32_bf16 v[64:67], v[186:189], v[240:243], v[64:67]
	s_barrier
	ds_read_b128 v[190:193], v169 offset:16384
	ds_read_b128 v[194:197], v169 offset:17408
	ds_read_b128 v[198:201], v169 offset:18432
	ds_read_b128 v[202:205], v169 offset:19456
	ds_read_b128 v[220:223], v169 offset:20480
	ds_read_b128 v[224:227], v169 offset:21504
	ds_read_b128 v[228:231], v169 offset:22528
	ds_read_b128 v[240:243], v169 offset:23552
	s_mov_b32 m0, s7
	s_nop 0
	buffer_load_dwordx4 v166, s[28:31], s55 offen lds
	s_add_i32 s57, s55, 0x80000
	s_mov_b32 m0, s8
	s_nop 0
	buffer_load_dwordx4 v167, s[28:31], s55 offen lds
	s_nop 7
	s_mov_b32 m0, s9
	s_nop 0
	buffer_load_dwordx4 v166, s[28:31], s57 offen lds
	s_nop 7
	s_mov_b32 m0, s10
	s_nop 0
	buffer_load_dwordx4 v167, s[28:31], s57 offen lds
	s_nop 7
	s_mov_b32 m0, s6
	s_nop 0
	buffer_load_dwordx4 v166, s[24:27], s56 offen lds
	s_nop 7
	s_mov_b32 m0, s11
	s_nop 0
	buffer_load_dwordx4 v167, s[24:27], s56 offen lds
	s_waitcnt vmcnt(24)
	s_waitcnt lgkmcnt(0)
	s_barrier
	s_waitcnt lgkmcnt(7)
	v_mfma_f32_16x16x32_bf16 v[60:63], v[152:155], v[190:193], 0
	v_mfma_f32_16x16x32_bf16 v[52:55], v[160:163], v[190:193], 0
	s_waitcnt lgkmcnt(5)
	v_mfma_f32_16x16x32_bf16 v[44:47], v[152:155], v[198:201], 0
	v_mfma_f32_16x16x32_bf16 v[36:39], v[160:163], v[198:201], 0
	s_waitcnt lgkmcnt(3)
	v_mfma_f32_16x16x32_bf16 v[28:31], v[152:155], v[220:223], 0
	v_mfma_f32_16x16x32_bf16 v[20:23], v[160:163], v[220:223], 0
	s_waitcnt lgkmcnt(1)
	v_mfma_f32_16x16x32_bf16 v[12:15], v[152:155], v[228:231], 0
	v_mfma_f32_16x16x32_bf16 v[4:7], v[160:163], v[228:231], 0
	v_mfma_f32_16x16x32_bf16 v[60:63], v[156:159], v[194:197], v[60:63]
	v_mfma_f32_16x16x32_bf16 v[52:55], v[170:173], v[194:197], v[52:55]
	v_mfma_f32_16x16x32_bf16 v[44:47], v[156:159], v[202:205], v[44:47]
	v_mfma_f32_16x16x32_bf16 v[36:39], v[170:173], v[202:205], v[36:39]
	v_mfma_f32_16x16x32_bf16 v[28:31], v[156:159], v[224:227], v[28:31]
	v_mfma_f32_16x16x32_bf16 v[20:23], v[170:173], v[224:227], v[20:23]
	s_waitcnt lgkmcnt(0)
	v_mfma_f32_16x16x32_bf16 v[12:15], v[156:159], v[240:243], v[12:15]
	v_mfma_f32_16x16x32_bf16 v[4:7], v[170:173], v[240:243], v[4:7]
	v_mfma_f32_16x16x32_bf16 v[56:59], v[174:177], v[190:193], 0
	v_mfma_f32_16x16x32_bf16 v[48:51], v[182:185], v[190:193], 0
	v_mfma_f32_16x16x32_bf16 v[40:43], v[174:177], v[198:201], 0
	v_mfma_f32_16x16x32_bf16 v[32:35], v[182:185], v[198:201], 0
	v_mfma_f32_16x16x32_bf16 v[24:27], v[174:177], v[220:223], 0
	v_mfma_f32_16x16x32_bf16 v[16:19], v[182:185], v[220:223], 0
	v_mfma_f32_16x16x32_bf16 v[8:11], v[174:177], v[228:231], 0
	v_mfma_f32_16x16x32_bf16 v[0:3], v[182:185], v[228:231], 0
	v_mfma_f32_16x16x32_bf16 v[56:59], v[178:181], v[194:197], v[56:59]
	v_mfma_f32_16x16x32_bf16 v[48:51], v[186:189], v[194:197], v[48:51]
	v_mfma_f32_16x16x32_bf16 v[40:43], v[178:181], v[202:205], v[40:43]
	v_mfma_f32_16x16x32_bf16 v[32:35], v[186:189], v[202:205], v[32:35]
	v_mfma_f32_16x16x32_bf16 v[24:27], v[178:181], v[224:227], v[24:27]
	v_mfma_f32_16x16x32_bf16 v[16:19], v[186:189], v[224:227], v[16:19]
	v_mfma_f32_16x16x32_bf16 v[8:11], v[178:181], v[240:243], v[8:11]
	v_mfma_f32_16x16x32_bf16 v[0:3], v[186:189], v[240:243], v[0:3]
	s_barrier
	v_add_u32_e32 v164, 0x18000, v168
	ds_read_b128 v[152:155], v164
	ds_read_b128 v[156:159], v164 offset:1024
	ds_read_b128 v[160:163], v164 offset:2048
	ds_read_b128 v[170:173], v164 offset:3072
	v_add_u32_e32 v164, 0x1c000, v168
	ds_read_b128 v[174:177], v164
	ds_read_b128 v[178:181], v164 offset:1024
	ds_read_b128 v[182:185], v164 offset:2048
	ds_read_b128 v[186:189], v164 offset:3072
	ds_read_b128 v[190:193], v169 offset:32768
	ds_read_b128 v[194:197], v169 offset:33792
	ds_read_b128 v[198:201], v169 offset:34816
	ds_read_b128 v[202:205], v169 offset:35840
	ds_read_b128 v[220:223], v169 offset:36864
	ds_read_b128 v[224:227], v169 offset:37888
	ds_read_b128 v[228:231], v169 offset:38912
	ds_read_b128 v[240:243], v169 offset:39936
	s_add_i32 s56, s56, 0x80000
	s_mov_b32 m0, s12
	s_nop 0
	buffer_load_dwordx4 v166, s[24:27], s56 offen lds
	s_nop 7
	s_mov_b32 m0, s13
	s_nop 0
	buffer_load_dwordx4 v167, s[24:27], s56 offen lds
	s_waitcnt vmcnt(8)
	s_waitcnt lgkmcnt(0)
	s_barrier
	s_waitcnt lgkmcnt(7)
	v_mfma_f32_16x16x32_bf16 v[148:151], v[152:155], v[190:193], v[148:151]
	v_mfma_f32_16x16x32_bf16 v[140:143], v[160:163], v[190:193], v[140:143]
	s_waitcnt lgkmcnt(5)
	v_mfma_f32_16x16x32_bf16 v[132:135], v[152:155], v[198:201], v[132:135]
	v_mfma_f32_16x16x32_bf16 v[124:127], v[160:163], v[198:201], v[124:127]
	s_waitcnt lgkmcnt(3)
	v_mfma_f32_16x16x32_bf16 v[116:119], v[152:155], v[220:223], v[116:119]
	v_mfma_f32_16x16x32_bf16 v[108:111], v[160:163], v[220:223], v[108:111]
	s_waitcnt lgkmcnt(1)
	v_mfma_f32_16x16x32_bf16 v[76:79], v[152:155], v[228:231], v[76:79]
	v_mfma_f32_16x16x32_bf16 v[68:71], v[160:163], v[228:231], v[68:71]
	v_mfma_f32_16x16x32_bf16 v[148:151], v[156:159], v[194:197], v[148:151]
	v_mfma_f32_16x16x32_bf16 v[140:143], v[170:173], v[194:197], v[140:143]
	v_mfma_f32_16x16x32_bf16 v[132:135], v[156:159], v[202:205], v[132:135]
	v_mfma_f32_16x16x32_bf16 v[124:127], v[170:173], v[202:205], v[124:127]
	v_mfma_f32_16x16x32_bf16 v[116:119], v[156:159], v[224:227], v[116:119]
	v_mfma_f32_16x16x32_bf16 v[108:111], v[170:173], v[224:227], v[108:111]
	s_waitcnt lgkmcnt(0)
	v_mfma_f32_16x16x32_bf16 v[76:79], v[156:159], v[240:243], v[76:79]
	v_mfma_f32_16x16x32_bf16 v[68:71], v[170:173], v[240:243], v[68:71]
	v_mfma_f32_16x16x32_bf16 v[144:147], v[174:177], v[190:193], v[144:147]
	v_mfma_f32_16x16x32_bf16 v[136:139], v[182:185], v[190:193], v[136:139]
	v_mfma_f32_16x16x32_bf16 v[128:131], v[174:177], v[198:201], v[128:131]
	v_mfma_f32_16x16x32_bf16 v[120:123], v[182:185], v[198:201], v[120:123]
	v_mfma_f32_16x16x32_bf16 v[112:115], v[174:177], v[220:223], v[112:115]
	v_mfma_f32_16x16x32_bf16 v[104:107], v[182:185], v[220:223], v[104:107]
	v_mfma_f32_16x16x32_bf16 v[72:75], v[174:177], v[228:231], v[72:75]
	v_mfma_f32_16x16x32_bf16 v[64:67], v[182:185], v[228:231], v[64:67]
	v_mfma_f32_16x16x32_bf16 v[144:147], v[178:181], v[194:197], v[144:147]
	v_mfma_f32_16x16x32_bf16 v[136:139], v[186:189], v[194:197], v[136:139]
	v_mfma_f32_16x16x32_bf16 v[128:131], v[178:181], v[202:205], v[128:131]
	v_mfma_f32_16x16x32_bf16 v[120:123], v[186:189], v[202:205], v[120:123]
	v_mfma_f32_16x16x32_bf16 v[112:115], v[178:181], v[224:227], v[112:115]
	v_mfma_f32_16x16x32_bf16 v[104:107], v[186:189], v[224:227], v[104:107]
	v_mfma_f32_16x16x32_bf16 v[72:75], v[178:181], v[240:243], v[72:75]
	v_mfma_f32_16x16x32_bf16 v[64:67], v[186:189], v[240:243], v[64:67]
	s_barrier
	ds_read_b128 v[190:193], v169 offset:49152
	ds_read_b128 v[194:197], v169 offset:50176
	ds_read_b128 v[198:201], v169 offset:51200
	ds_read_b128 v[202:205], v169 offset:52224
	ds_read_b128 v[220:223], v169 offset:53248
	ds_read_b128 v[224:227], v169 offset:54272
	ds_read_b128 v[228:231], v169 offset:55296
	ds_read_b128 v[240:243], v169 offset:56320
	s_or_b32 s56, s55, 0x4000
	s_mov_b32 m0, s16
	s_nop 0
	buffer_load_dwordx4 v166, s[28:31], s56 offen lds
	s_add_i32 s55, s55, 0x84000
	s_mov_b32 m0, s17
	s_nop 0
	buffer_load_dwordx4 v167, s[28:31], s56 offen lds
	s_nop 7
	s_mov_b32 m0, s34
	s_nop 0
	buffer_load_dwordx4 v166, s[28:31], s55 offen lds
	s_nop 7
	s_mov_b32 m0, s40
	s_nop 0
	buffer_load_dwordx4 v167, s[28:31], s55 offen lds
	s_nop 7
	s_mov_b32 m0, s18
	s_nop 0
	buffer_load_dwordx4 v166, s[24:27], s53 offen lds
	s_nop 7
	s_mov_b32 m0, s19
	s_nop 0
	buffer_load_dwordx4 v167, s[24:27], s53 offen lds
	s_waitcnt vmcnt(8)
	s_waitcnt lgkmcnt(0)
	s_barrier
	s_waitcnt lgkmcnt(7)
	v_mfma_f32_16x16x32_bf16 v[60:63], v[152:155], v[190:193], v[60:63]
	v_mfma_f32_16x16x32_bf16 v[52:55], v[160:163], v[190:193], v[52:55]
	s_waitcnt lgkmcnt(5)
	v_mfma_f32_16x16x32_bf16 v[44:47], v[152:155], v[198:201], v[44:47]
	v_mfma_f32_16x16x32_bf16 v[36:39], v[160:163], v[198:201], v[36:39]
	s_waitcnt lgkmcnt(3)
	v_mfma_f32_16x16x32_bf16 v[28:31], v[152:155], v[220:223], v[28:31]
	v_mfma_f32_16x16x32_bf16 v[20:23], v[160:163], v[220:223], v[20:23]
	s_waitcnt lgkmcnt(1)
	v_mfma_f32_16x16x32_bf16 v[12:15], v[152:155], v[228:231], v[12:15]
	v_mfma_f32_16x16x32_bf16 v[4:7], v[160:163], v[228:231], v[4:7]
	v_mfma_f32_16x16x32_bf16 v[60:63], v[156:159], v[194:197], v[60:63]
	v_mfma_f32_16x16x32_bf16 v[52:55], v[170:173], v[194:197], v[52:55]
	v_mfma_f32_16x16x32_bf16 v[44:47], v[156:159], v[202:205], v[44:47]
	v_mfma_f32_16x16x32_bf16 v[36:39], v[170:173], v[202:205], v[36:39]
	v_mfma_f32_16x16x32_bf16 v[28:31], v[156:159], v[224:227], v[28:31]
	v_mfma_f32_16x16x32_bf16 v[20:23], v[170:173], v[224:227], v[20:23]
	s_waitcnt lgkmcnt(0)
	v_mfma_f32_16x16x32_bf16 v[12:15], v[156:159], v[240:243], v[12:15]
	v_mfma_f32_16x16x32_bf16 v[4:7], v[170:173], v[240:243], v[4:7]
	v_mfma_f32_16x16x32_bf16 v[56:59], v[174:177], v[190:193], v[56:59]
	v_mfma_f32_16x16x32_bf16 v[48:51], v[182:185], v[190:193], v[48:51]
	v_mfma_f32_16x16x32_bf16 v[40:43], v[174:177], v[198:201], v[40:43]
	v_mfma_f32_16x16x32_bf16 v[32:35], v[182:185], v[198:201], v[32:35]
	v_mfma_f32_16x16x32_bf16 v[24:27], v[174:177], v[220:223], v[24:27]
	v_mfma_f32_16x16x32_bf16 v[16:19], v[182:185], v[220:223], v[16:19]
	v_mfma_f32_16x16x32_bf16 v[8:11], v[174:177], v[228:231], v[8:11]
	v_mfma_f32_16x16x32_bf16 v[0:3], v[182:185], v[228:231], v[0:3]
	v_mfma_f32_16x16x32_bf16 v[56:59], v[178:181], v[194:197], v[56:59]
	v_mfma_f32_16x16x32_bf16 v[48:51], v[186:189], v[194:197], v[48:51]
	v_mfma_f32_16x16x32_bf16 v[40:43], v[178:181], v[202:205], v[40:43]
	v_mfma_f32_16x16x32_bf16 v[32:35], v[186:189], v[202:205], v[32:35]
	v_mfma_f32_16x16x32_bf16 v[24:27], v[178:181], v[224:227], v[24:27]
	v_mfma_f32_16x16x32_bf16 v[16:19], v[186:189], v[224:227], v[16:19]
	v_mfma_f32_16x16x32_bf16 v[8:11], v[178:181], v[240:243], v[8:11]
	v_mfma_f32_16x16x32_bf16 v[0:3], v[186:189], v[240:243], v[0:3]
	s_barrier
	s_add_i32 s52, s52, 2
	s_add_i32 s37, s37, 0x8000
	s_add_i32 s51, s51, 0x8000
.LBB0_795:
	v_add_u32_e32 v164, 0x10000, v168
	ds_read_b128 v[152:155], v164
	ds_read_b128 v[156:159], v164 offset:1024
	ds_read_b128 v[160:163], v164 offset:2048
	ds_read_b128 v[170:173], v164 offset:3072
	v_add_u32_e32 v164, 0x14000, v168
	ds_read_b128 v[174:177], v164
	ds_read_b128 v[178:181], v164 offset:1024
	ds_read_b128 v[182:185], v164 offset:2048
	ds_read_b128 v[186:189], v164 offset:3072
	s_add_i32 s53, s37, 0xfff84000
	s_cmp_eq_u32 s52, 28
	s_cselect_b32 s56, s4, s53
	s_cselect_b32 s55, s5, s51
	s_or_b32 s53, s56, 0x4000
	ds_read_b128 v[190:193], v169
	ds_read_b128 v[194:197], v169 offset:1024
	ds_read_b128 v[198:201], v169 offset:2048
	ds_read_b128 v[202:205], v169 offset:3072
	ds_read_b128 v[220:223], v169 offset:4096
	ds_read_b128 v[224:227], v169 offset:5120
	ds_read_b128 v[228:231], v169 offset:6144
	ds_read_b128 v[240:243], v169 offset:7168
	s_mov_b32 m0, s41
	s_nop 0
	buffer_load_dwordx4 v166, s[24:27], s37 offen lds
	s_nop 7
	s_mov_b32 m0, s42
	s_nop 0
	buffer_load_dwordx4 v167, s[24:27], s37 offen lds
	s_waitcnt vmcnt(8)
	s_waitcnt lgkmcnt(0)
	s_barrier
	s_waitcnt lgkmcnt(7)
	v_mfma_f32_16x16x32_bf16 v[148:151], v[152:155], v[190:193], v[148:151]
	v_mfma_f32_16x16x32_bf16 v[140:143], v[160:163], v[190:193], v[140:143]
	s_waitcnt lgkmcnt(5)
	v_mfma_f32_16x16x32_bf16 v[132:135], v[152:155], v[198:201], v[132:135]
	v_mfma_f32_16x16x32_bf16 v[124:127], v[160:163], v[198:201], v[124:127]
	s_waitcnt lgkmcnt(3)
	v_mfma_f32_16x16x32_bf16 v[116:119], v[152:155], v[220:223], v[116:119]
	v_mfma_f32_16x16x32_bf16 v[108:111], v[160:163], v[220:223], v[108:111]
	s_waitcnt lgkmcnt(1)
	v_mfma_f32_16x16x32_bf16 v[76:79], v[152:155], v[228:231], v[76:79]
	v_mfma_f32_16x16x32_bf16 v[68:71], v[160:163], v[228:231], v[68:71]
	v_mfma_f32_16x16x32_bf16 v[148:151], v[156:159], v[194:197], v[148:151]
	v_mfma_f32_16x16x32_bf16 v[140:143], v[170:173], v[194:197], v[140:143]
	v_mfma_f32_16x16x32_bf16 v[132:135], v[156:159], v[202:205], v[132:135]
	v_mfma_f32_16x16x32_bf16 v[124:127], v[170:173], v[202:205], v[124:127]
	v_mfma_f32_16x16x32_bf16 v[116:119], v[156:159], v[224:227], v[116:119]
	v_mfma_f32_16x16x32_bf16 v[108:111], v[170:173], v[224:227], v[108:111]
	s_waitcnt lgkmcnt(0)
	v_mfma_f32_16x16x32_bf16 v[76:79], v[156:159], v[240:243], v[76:79]
	v_mfma_f32_16x16x32_bf16 v[68:71], v[170:173], v[240:243], v[68:71]
	v_mfma_f32_16x16x32_bf16 v[144:147], v[174:177], v[190:193], v[144:147]
	v_mfma_f32_16x16x32_bf16 v[136:139], v[182:185], v[190:193], v[136:139]
	v_mfma_f32_16x16x32_bf16 v[128:131], v[174:177], v[198:201], v[128:131]
	v_mfma_f32_16x16x32_bf16 v[120:123], v[182:185], v[198:201], v[120:123]
	v_mfma_f32_16x16x32_bf16 v[112:115], v[174:177], v[220:223], v[112:115]
	v_mfma_f32_16x16x32_bf16 v[104:107], v[182:185], v[220:223], v[104:107]
	v_mfma_f32_16x16x32_bf16 v[72:75], v[174:177], v[228:231], v[72:75]
	v_mfma_f32_16x16x32_bf16 v[64:67], v[182:185], v[228:231], v[64:67]
	v_mfma_f32_16x16x32_bf16 v[144:147], v[178:181], v[194:197], v[144:147]
	v_mfma_f32_16x16x32_bf16 v[136:139], v[186:189], v[194:197], v[136:139]
	v_mfma_f32_16x16x32_bf16 v[128:131], v[178:181], v[202:205], v[128:131]
	v_mfma_f32_16x16x32_bf16 v[120:123], v[186:189], v[202:205], v[120:123]
	v_mfma_f32_16x16x32_bf16 v[112:115], v[178:181], v[224:227], v[112:115]
	v_mfma_f32_16x16x32_bf16 v[104:107], v[186:189], v[224:227], v[104:107]
	v_mfma_f32_16x16x32_bf16 v[72:75], v[178:181], v[240:243], v[72:75]
	v_mfma_f32_16x16x32_bf16 v[64:67], v[186:189], v[240:243], v[64:67]
	s_barrier
	ds_read_b128 v[190:193], v169 offset:16384
	ds_read_b128 v[194:197], v169 offset:17408
	ds_read_b128 v[198:201], v169 offset:18432
	ds_read_b128 v[202:205], v169 offset:19456
	ds_read_b128 v[220:223], v169 offset:20480
	ds_read_b128 v[224:227], v169 offset:21504
	ds_read_b128 v[228:231], v169 offset:22528
	ds_read_b128 v[240:243], v169 offset:23552
	s_mov_b32 m0, s7
	s_nop 0
	buffer_load_dwordx4 v166, s[28:31], s55 offen lds
	s_add_i32 s57, s55, 0x80000
	s_mov_b32 m0, s8
	s_nop 0
	buffer_load_dwordx4 v167, s[28:31], s55 offen lds
	s_nop 7
	s_mov_b32 m0, s9
	s_nop 0
	buffer_load_dwordx4 v166, s[28:31], s57 offen lds
	s_nop 7
	s_mov_b32 m0, s10
	s_nop 0
	buffer_load_dwordx4 v167, s[28:31], s57 offen lds
	s_nop 7
	s_mov_b32 m0, s6
	s_nop 0
	buffer_load_dwordx4 v166, s[24:27], s56 offen lds
	s_nop 7
	s_mov_b32 m0, s11
	s_nop 0
	buffer_load_dwordx4 v167, s[24:27], s56 offen lds
	s_waitcnt vmcnt(8)
	s_waitcnt lgkmcnt(0)
	s_barrier
	s_waitcnt lgkmcnt(7)
	v_mfma_f32_16x16x32_bf16 v[60:63], v[152:155], v[190:193], v[60:63]
	v_mfma_f32_16x16x32_bf16 v[52:55], v[160:163], v[190:193], v[52:55]
	s_waitcnt lgkmcnt(5)
	v_mfma_f32_16x16x32_bf16 v[44:47], v[152:155], v[198:201], v[44:47]
	v_mfma_f32_16x16x32_bf16 v[36:39], v[160:163], v[198:201], v[36:39]
	s_waitcnt lgkmcnt(3)
	v_mfma_f32_16x16x32_bf16 v[28:31], v[152:155], v[220:223], v[28:31]
	v_mfma_f32_16x16x32_bf16 v[20:23], v[160:163], v[220:223], v[20:23]
	s_waitcnt lgkmcnt(1)
	v_mfma_f32_16x16x32_bf16 v[12:15], v[152:155], v[228:231], v[12:15]
	v_mfma_f32_16x16x32_bf16 v[4:7], v[160:163], v[228:231], v[4:7]
	v_mfma_f32_16x16x32_bf16 v[60:63], v[156:159], v[194:197], v[60:63]
	v_mfma_f32_16x16x32_bf16 v[52:55], v[170:173], v[194:197], v[52:55]
	v_mfma_f32_16x16x32_bf16 v[44:47], v[156:159], v[202:205], v[44:47]
	v_mfma_f32_16x16x32_bf16 v[36:39], v[170:173], v[202:205], v[36:39]
	v_mfma_f32_16x16x32_bf16 v[28:31], v[156:159], v[224:227], v[28:31]
	v_mfma_f32_16x16x32_bf16 v[20:23], v[170:173], v[224:227], v[20:23]
	s_waitcnt lgkmcnt(0)
	v_mfma_f32_16x16x32_bf16 v[12:15], v[156:159], v[240:243], v[12:15]
	v_mfma_f32_16x16x32_bf16 v[4:7], v[170:173], v[240:243], v[4:7]
	v_mfma_f32_16x16x32_bf16 v[56:59], v[174:177], v[190:193], v[56:59]
	v_mfma_f32_16x16x32_bf16 v[48:51], v[182:185], v[190:193], v[48:51]
	v_mfma_f32_16x16x32_bf16 v[40:43], v[174:177], v[198:201], v[40:43]
	v_mfma_f32_16x16x32_bf16 v[32:35], v[182:185], v[198:201], v[32:35]
	v_mfma_f32_16x16x32_bf16 v[24:27], v[174:177], v[220:223], v[24:27]
	v_mfma_f32_16x16x32_bf16 v[16:19], v[182:185], v[220:223], v[16:19]
	v_mfma_f32_16x16x32_bf16 v[8:11], v[174:177], v[228:231], v[8:11]
	v_mfma_f32_16x16x32_bf16 v[0:3], v[182:185], v[228:231], v[0:3]
	v_mfma_f32_16x16x32_bf16 v[56:59], v[178:181], v[194:197], v[56:59]
	v_mfma_f32_16x16x32_bf16 v[48:51], v[186:189], v[194:197], v[48:51]
	v_mfma_f32_16x16x32_bf16 v[40:43], v[178:181], v[202:205], v[40:43]
	v_mfma_f32_16x16x32_bf16 v[32:35], v[186:189], v[202:205], v[32:35]
	v_mfma_f32_16x16x32_bf16 v[24:27], v[178:181], v[224:227], v[24:27]
	v_mfma_f32_16x16x32_bf16 v[16:19], v[186:189], v[224:227], v[16:19]
	v_mfma_f32_16x16x32_bf16 v[8:11], v[178:181], v[240:243], v[8:11]
	v_mfma_f32_16x16x32_bf16 v[0:3], v[186:189], v[240:243], v[0:3]
	s_barrier
	v_add_u32_e32 v164, 0x18000, v168
	ds_read_b128 v[152:155], v164
	ds_read_b128 v[156:159], v164 offset:1024
	ds_read_b128 v[160:163], v164 offset:2048
	ds_read_b128 v[170:173], v164 offset:3072
	v_add_u32_e32 v164, 0x1c000, v168
	ds_read_b128 v[174:177], v164
	ds_read_b128 v[178:181], v164 offset:1024
	ds_read_b128 v[182:185], v164 offset:2048
	ds_read_b128 v[186:189], v164 offset:3072
	ds_read_b128 v[190:193], v169 offset:32768
	ds_read_b128 v[194:197], v169 offset:33792
	ds_read_b128 v[198:201], v169 offset:34816
	ds_read_b128 v[202:205], v169 offset:35840
	ds_read_b128 v[220:223], v169 offset:36864
	ds_read_b128 v[224:227], v169 offset:37888
	ds_read_b128 v[228:231], v169 offset:38912
	ds_read_b128 v[240:243], v169 offset:39936
	s_add_i32 s56, s56, 0x80000
	s_mov_b32 m0, s12
	s_nop 0
	buffer_load_dwordx4 v166, s[24:27], s56 offen lds
	s_nop 7
	s_mov_b32 m0, s13
	s_nop 0
	buffer_load_dwordx4 v167, s[24:27], s56 offen lds
	s_waitcnt vmcnt(8)
	s_waitcnt lgkmcnt(0)
	s_barrier
	s_waitcnt lgkmcnt(7)
	v_mfma_f32_16x16x32_bf16 v[148:151], v[152:155], v[190:193], v[148:151]
	v_mfma_f32_16x16x32_bf16 v[140:143], v[160:163], v[190:193], v[140:143]
	s_waitcnt lgkmcnt(5)
	v_mfma_f32_16x16x32_bf16 v[132:135], v[152:155], v[198:201], v[132:135]
	v_mfma_f32_16x16x32_bf16 v[124:127], v[160:163], v[198:201], v[124:127]
	s_waitcnt lgkmcnt(3)
	v_mfma_f32_16x16x32_bf16 v[116:119], v[152:155], v[220:223], v[116:119]
	v_mfma_f32_16x16x32_bf16 v[108:111], v[160:163], v[220:223], v[108:111]
	s_waitcnt lgkmcnt(1)
	v_mfma_f32_16x16x32_bf16 v[76:79], v[152:155], v[228:231], v[76:79]
	v_mfma_f32_16x16x32_bf16 v[68:71], v[160:163], v[228:231], v[68:71]
	v_mfma_f32_16x16x32_bf16 v[148:151], v[156:159], v[194:197], v[148:151]
	v_mfma_f32_16x16x32_bf16 v[140:143], v[170:173], v[194:197], v[140:143]
	v_mfma_f32_16x16x32_bf16 v[132:135], v[156:159], v[202:205], v[132:135]
	v_mfma_f32_16x16x32_bf16 v[124:127], v[170:173], v[202:205], v[124:127]
	v_mfma_f32_16x16x32_bf16 v[116:119], v[156:159], v[224:227], v[116:119]
	v_mfma_f32_16x16x32_bf16 v[108:111], v[170:173], v[224:227], v[108:111]
	s_waitcnt lgkmcnt(0)
	v_mfma_f32_16x16x32_bf16 v[76:79], v[156:159], v[240:243], v[76:79]
	v_mfma_f32_16x16x32_bf16 v[68:71], v[170:173], v[240:243], v[68:71]
	v_mfma_f32_16x16x32_bf16 v[144:147], v[174:177], v[190:193], v[144:147]
	v_mfma_f32_16x16x32_bf16 v[136:139], v[182:185], v[190:193], v[136:139]
	v_mfma_f32_16x16x32_bf16 v[128:131], v[174:177], v[198:201], v[128:131]
	v_mfma_f32_16x16x32_bf16 v[120:123], v[182:185], v[198:201], v[120:123]
	v_mfma_f32_16x16x32_bf16 v[112:115], v[174:177], v[220:223], v[112:115]
	v_mfma_f32_16x16x32_bf16 v[104:107], v[182:185], v[220:223], v[104:107]
	v_mfma_f32_16x16x32_bf16 v[72:75], v[174:177], v[228:231], v[72:75]
	v_mfma_f32_16x16x32_bf16 v[64:67], v[182:185], v[228:231], v[64:67]
	v_mfma_f32_16x16x32_bf16 v[144:147], v[178:181], v[194:197], v[144:147]
	v_mfma_f32_16x16x32_bf16 v[136:139], v[186:189], v[194:197], v[136:139]
	v_mfma_f32_16x16x32_bf16 v[128:131], v[178:181], v[202:205], v[128:131]
	v_mfma_f32_16x16x32_bf16 v[120:123], v[186:189], v[202:205], v[120:123]
	v_mfma_f32_16x16x32_bf16 v[112:115], v[178:181], v[224:227], v[112:115]
	v_mfma_f32_16x16x32_bf16 v[104:107], v[186:189], v[224:227], v[104:107]
	v_mfma_f32_16x16x32_bf16 v[72:75], v[178:181], v[240:243], v[72:75]
	v_mfma_f32_16x16x32_bf16 v[64:67], v[186:189], v[240:243], v[64:67]
	s_barrier
	ds_read_b128 v[190:193], v169 offset:49152
	ds_read_b128 v[194:197], v169 offset:50176
	ds_read_b128 v[198:201], v169 offset:51200
	ds_read_b128 v[202:205], v169 offset:52224
	ds_read_b128 v[220:223], v169 offset:53248
	ds_read_b128 v[224:227], v169 offset:54272
	ds_read_b128 v[228:231], v169 offset:55296
	ds_read_b128 v[240:243], v169 offset:56320
	s_or_b32 s56, s55, 0x4000
	s_mov_b32 m0, s16
	s_nop 0
	buffer_load_dwordx4 v166, s[28:31], s56 offen lds
	s_add_i32 s55, s55, 0x84000
	s_mov_b32 m0, s17
	s_nop 0
	buffer_load_dwordx4 v167, s[28:31], s56 offen lds
	s_nop 7
	s_mov_b32 m0, s34
	s_nop 0
	buffer_load_dwordx4 v166, s[28:31], s55 offen lds
	s_nop 7
	s_mov_b32 m0, s40
	s_nop 0
	buffer_load_dwordx4 v167, s[28:31], s55 offen lds
	s_nop 7
	s_mov_b32 m0, s18
	s_nop 0
	buffer_load_dwordx4 v166, s[24:27], s53 offen lds
	s_nop 7
	s_mov_b32 m0, s19
	s_nop 0
	buffer_load_dwordx4 v167, s[24:27], s53 offen lds
	s_waitcnt vmcnt(8)
	s_waitcnt lgkmcnt(0)
	s_barrier
	s_waitcnt lgkmcnt(7)
	v_mfma_f32_16x16x32_bf16 v[60:63], v[152:155], v[190:193], v[60:63]
	v_mfma_f32_16x16x32_bf16 v[52:55], v[160:163], v[190:193], v[52:55]
	s_waitcnt lgkmcnt(5)
	v_mfma_f32_16x16x32_bf16 v[44:47], v[152:155], v[198:201], v[44:47]
	v_mfma_f32_16x16x32_bf16 v[36:39], v[160:163], v[198:201], v[36:39]
	s_waitcnt lgkmcnt(3)
	v_mfma_f32_16x16x32_bf16 v[28:31], v[152:155], v[220:223], v[28:31]
	v_mfma_f32_16x16x32_bf16 v[20:23], v[160:163], v[220:223], v[20:23]
	s_waitcnt lgkmcnt(1)
	v_mfma_f32_16x16x32_bf16 v[12:15], v[152:155], v[228:231], v[12:15]
	v_mfma_f32_16x16x32_bf16 v[4:7], v[160:163], v[228:231], v[4:7]
	v_mfma_f32_16x16x32_bf16 v[60:63], v[156:159], v[194:197], v[60:63]
	v_mfma_f32_16x16x32_bf16 v[52:55], v[170:173], v[194:197], v[52:55]
	v_mfma_f32_16x16x32_bf16 v[44:47], v[156:159], v[202:205], v[44:47]
	v_mfma_f32_16x16x32_bf16 v[36:39], v[170:173], v[202:205], v[36:39]
	v_mfma_f32_16x16x32_bf16 v[28:31], v[156:159], v[224:227], v[28:31]
	v_mfma_f32_16x16x32_bf16 v[20:23], v[170:173], v[224:227], v[20:23]
	s_waitcnt lgkmcnt(0)
	v_mfma_f32_16x16x32_bf16 v[12:15], v[156:159], v[240:243], v[12:15]
	v_mfma_f32_16x16x32_bf16 v[4:7], v[170:173], v[240:243], v[4:7]
	v_mfma_f32_16x16x32_bf16 v[56:59], v[174:177], v[190:193], v[56:59]
	v_mfma_f32_16x16x32_bf16 v[48:51], v[182:185], v[190:193], v[48:51]
	v_mfma_f32_16x16x32_bf16 v[40:43], v[174:177], v[198:201], v[40:43]
	v_mfma_f32_16x16x32_bf16 v[32:35], v[182:185], v[198:201], v[32:35]
	v_mfma_f32_16x16x32_bf16 v[24:27], v[174:177], v[220:223], v[24:27]
	v_mfma_f32_16x16x32_bf16 v[16:19], v[182:185], v[220:223], v[16:19]
	v_mfma_f32_16x16x32_bf16 v[8:11], v[174:177], v[228:231], v[8:11]
	v_mfma_f32_16x16x32_bf16 v[0:3], v[182:185], v[228:231], v[0:3]
	v_mfma_f32_16x16x32_bf16 v[56:59], v[178:181], v[194:197], v[56:59]
	v_mfma_f32_16x16x32_bf16 v[48:51], v[186:189], v[194:197], v[48:51]
	v_mfma_f32_16x16x32_bf16 v[40:43], v[178:181], v[202:205], v[40:43]
	v_mfma_f32_16x16x32_bf16 v[32:35], v[186:189], v[202:205], v[32:35]
	v_mfma_f32_16x16x32_bf16 v[24:27], v[178:181], v[224:227], v[24:27]
	v_mfma_f32_16x16x32_bf16 v[16:19], v[186:189], v[224:227], v[16:19]
	v_mfma_f32_16x16x32_bf16 v[8:11], v[178:181], v[240:243], v[8:11]
	v_mfma_f32_16x16x32_bf16 v[0:3], v[186:189], v[240:243], v[0:3]
	s_barrier
	s_add_i32 s52, s52, 2
	s_add_i32 s37, s37, 0x8000
	s_add_i32 s51, s51, 0x8000
	s_cmp_gt_u32 s52, 29
	s_cbranch_scc0 .LBB0_795

.Lnb_p6:
	s_add_i32 s11, s8, 0xffea4000
	s_cmpk_eq_i32 s10, 0x54
	s_cselect_b32 s13, s6, s11
	s_cselect_b32 s12, s7, s9
	s_or_b32 s11, s13, 0x4000
	s_mov_b32 m0, s87
	s_nop 0
	buffer_load_dwordx4 v220, s[20:23], s8 offen lds
	s_nop 7
	s_mov_b32 m0, s89
	s_nop 0
	buffer_load_dwordx4 v221, s[20:23], s8 offen lds
	s_waitcnt vmcnt(24)
	s_waitcnt lgkmcnt(0)
	s_barrier
	s_waitcnt lgkmcnt(7)
	v_mfma_f32_16x16x32_bf16 v[164:167], v[128:131], v[184:187], 0
	v_mfma_f32_16x16x32_bf16 v[160:163], v[152:155], v[184:187], 0
	s_waitcnt lgkmcnt(5)
	v_mfma_f32_16x16x32_bf16 v[136:139], v[128:131], v[192:195], 0
	v_mfma_f32_16x16x32_bf16 v[132:135], v[152:155], v[192:195], 0
	s_waitcnt lgkmcnt(3)
	v_mfma_f32_16x16x32_bf16 v[116:119], v[128:131], v[200:203], 0
	v_mfma_f32_16x16x32_bf16 v[112:115], v[152:155], v[200:203], 0
	s_waitcnt lgkmcnt(1)
	v_mfma_f32_16x16x32_bf16 v[76:79], v[128:131], v[224:227], 0
	v_mfma_f32_16x16x32_bf16 v[72:75], v[152:155], v[224:227], 0
	v_mfma_f32_16x16x32_bf16 v[164:167], v[140:143], v[188:191], v[164:167]
	v_mfma_f32_16x16x32_bf16 v[160:163], v[156:159], v[188:191], v[160:163]
	v_mfma_f32_16x16x32_bf16 v[136:139], v[140:143], v[196:199], v[136:139]
	v_mfma_f32_16x16x32_bf16 v[132:135], v[156:159], v[196:199], v[132:135]
	v_mfma_f32_16x16x32_bf16 v[116:119], v[140:143], v[204:207], v[116:119]
	v_mfma_f32_16x16x32_bf16 v[112:115], v[156:159], v[204:207], v[112:115]
	s_waitcnt lgkmcnt(0)
	v_mfma_f32_16x16x32_bf16 v[76:79], v[140:143], v[228:231], v[76:79]
	v_mfma_f32_16x16x32_bf16 v[72:75], v[156:159], v[228:231], v[72:75]
	v_mfma_f32_16x16x32_bf16 v[148:151], v[168:171], v[184:187], 0
	v_mfma_f32_16x16x32_bf16 v[144:147], v[176:179], v[184:187], 0
	v_mfma_f32_16x16x32_bf16 v[124:127], v[168:171], v[192:195], 0
	v_mfma_f32_16x16x32_bf16 v[120:123], v[176:179], v[192:195], 0
	v_mfma_f32_16x16x32_bf16 v[108:111], v[168:171], v[200:203], 0
	v_mfma_f32_16x16x32_bf16 v[104:107], v[176:179], v[200:203], 0
	v_mfma_f32_16x16x32_bf16 v[68:71], v[168:171], v[224:227], 0
	v_mfma_f32_16x16x32_bf16 v[64:67], v[176:179], v[224:227], 0
	v_mfma_f32_16x16x32_bf16 v[148:151], v[172:175], v[188:191], v[148:151]
	v_mfma_f32_16x16x32_bf16 v[144:147], v[180:183], v[188:191], v[144:147]
	v_mfma_f32_16x16x32_bf16 v[124:127], v[172:175], v[196:199], v[124:127]
	v_mfma_f32_16x16x32_bf16 v[120:123], v[180:183], v[196:199], v[120:123]
	v_mfma_f32_16x16x32_bf16 v[108:111], v[172:175], v[204:207], v[108:111]
	v_mfma_f32_16x16x32_bf16 v[104:107], v[180:183], v[204:207], v[104:107]
	v_mfma_f32_16x16x32_bf16 v[68:71], v[172:175], v[228:231], v[68:71]
	v_mfma_f32_16x16x32_bf16 v[64:67], v[180:183], v[228:231], v[64:67]
	s_barrier
	ds_read_b128 v[184:187], v223 offset:16384
	ds_read_b128 v[188:191], v223 offset:17408
	ds_read_b128 v[192:195], v223 offset:18432
	ds_read_b128 v[196:199], v223 offset:19456
	ds_read_b128 v[200:203], v223 offset:20480
	ds_read_b128 v[204:207], v223 offset:21504
	ds_read_b128 v[224:227], v223 offset:22528
	ds_read_b128 v[228:231], v223 offset:23552
	s_mov_b32 m0, s51
	s_nop 0
	buffer_load_dwordx4 v220, s[52:55], s12 offen lds
	s_add_i32 s14, s12, 0x160000
	s_mov_b32 m0, s74
	s_nop 0
	buffer_load_dwordx4 v221, s[52:55], s12 offen lds
	s_nop 7
	s_mov_b32 m0, s75
	s_nop 0
	buffer_load_dwordx4 v220, s[52:55], s14 offen lds
	s_nop 7
	s_mov_b32 m0, s76
	s_nop 0
	buffer_load_dwordx4 v221, s[52:55], s14 offen lds
	s_nop 7
	s_mov_b32 m0, s31
	s_nop 0
	buffer_load_dwordx4 v220, s[20:23], s13 offen lds
	s_nop 7
	s_mov_b32 m0, s77
	s_nop 0
	buffer_load_dwordx4 v221, s[20:23], s13 offen lds
	s_waitcnt vmcnt(24)
	s_waitcnt lgkmcnt(0)
	s_barrier
	s_waitcnt lgkmcnt(7)
	v_mfma_f32_16x16x32_bf16 v[60:63], v[128:131], v[184:187], 0
	v_mfma_f32_16x16x32_bf16 v[56:59], v[152:155], v[184:187], 0
	s_waitcnt lgkmcnt(5)
	v_mfma_f32_16x16x32_bf16 v[44:47], v[128:131], v[192:195], 0
	v_mfma_f32_16x16x32_bf16 v[40:43], v[152:155], v[192:195], 0
	s_waitcnt lgkmcnt(3)
	v_mfma_f32_16x16x32_bf16 v[28:31], v[128:131], v[200:203], 0
	v_mfma_f32_16x16x32_bf16 v[24:27], v[152:155], v[200:203], 0
	s_waitcnt lgkmcnt(1)
	v_mfma_f32_16x16x32_bf16 v[12:15], v[128:131], v[224:227], 0
	v_mfma_f32_16x16x32_bf16 v[8:11], v[152:155], v[224:227], 0
	v_mfma_f32_16x16x32_bf16 v[60:63], v[140:143], v[188:191], v[60:63]
	v_mfma_f32_16x16x32_bf16 v[56:59], v[156:159], v[188:191], v[56:59]
	v_mfma_f32_16x16x32_bf16 v[44:47], v[140:143], v[196:199], v[44:47]
	v_mfma_f32_16x16x32_bf16 v[40:43], v[156:159], v[196:199], v[40:43]
	v_mfma_f32_16x16x32_bf16 v[28:31], v[140:143], v[204:207], v[28:31]
	v_mfma_f32_16x16x32_bf16 v[24:27], v[156:159], v[204:207], v[24:27]
	s_waitcnt lgkmcnt(0)
	v_mfma_f32_16x16x32_bf16 v[12:15], v[140:143], v[228:231], v[12:15]
	v_mfma_f32_16x16x32_bf16 v[8:11], v[156:159], v[228:231], v[8:11]
	v_mfma_f32_16x16x32_bf16 v[52:55], v[168:171], v[184:187], 0
	v_mfma_f32_16x16x32_bf16 v[48:51], v[176:179], v[184:187], 0
	v_mfma_f32_16x16x32_bf16 v[36:39], v[168:171], v[192:195], 0
	v_mfma_f32_16x16x32_bf16 v[32:35], v[176:179], v[192:195], 0
	v_mfma_f32_16x16x32_bf16 v[20:23], v[168:171], v[200:203], 0
	v_mfma_f32_16x16x32_bf16 v[16:19], v[176:179], v[200:203], 0
	v_mfma_f32_16x16x32_bf16 v[4:7], v[168:171], v[224:227], 0
	v_mfma_f32_16x16x32_bf16 v[0:3], v[176:179], v[224:227], 0
	v_mfma_f32_16x16x32_bf16 v[52:55], v[172:175], v[188:191], v[52:55]
	v_mfma_f32_16x16x32_bf16 v[48:51], v[180:183], v[188:191], v[48:51]
	v_mfma_f32_16x16x32_bf16 v[36:39], v[172:175], v[196:199], v[36:39]
	v_mfma_f32_16x16x32_bf16 v[32:35], v[180:183], v[196:199], v[32:35]
	v_mfma_f32_16x16x32_bf16 v[20:23], v[172:175], v[204:207], v[20:23]
	v_mfma_f32_16x16x32_bf16 v[16:19], v[180:183], v[204:207], v[16:19]
	v_mfma_f32_16x16x32_bf16 v[4:7], v[172:175], v[228:231], v[4:7]
	v_mfma_f32_16x16x32_bf16 v[0:3], v[180:183], v[228:231], v[0:3]
	s_barrier
	v_add_u32_e32 v156, 0x18000, v222
	v_add_u32_e32 v180, 0x1c000, v222
	ds_read_b128 v[128:131], v156
	ds_read_b128 v[140:143], v156 offset:1024
	ds_read_b128 v[152:155], v156 offset:2048
	ds_read_b128 v[156:159], v156 offset:3072
	ds_read_b128 v[168:171], v180
	ds_read_b128 v[172:175], v180 offset:1024
	ds_read_b128 v[176:179], v180 offset:2048
	ds_read_b128 v[180:183], v180 offset:3072
	ds_read_b128 v[184:187], v223 offset:32768
	ds_read_b128 v[188:191], v223 offset:33792
	ds_read_b128 v[192:195], v223 offset:34816
	ds_read_b128 v[196:199], v223 offset:35840
	ds_read_b128 v[200:203], v223 offset:36864
	ds_read_b128 v[204:207], v223 offset:37888
	ds_read_b128 v[224:227], v223 offset:38912
	ds_read_b128 v[228:231], v223 offset:39936
	s_add_i32 s13, s13, 0x160000
	s_mov_b32 m0, s78
	s_nop 0
	buffer_load_dwordx4 v220, s[20:23], s13 offen lds
	s_nop 7
	s_mov_b32 m0, s79
	s_nop 0
	buffer_load_dwordx4 v221, s[20:23], s13 offen lds
	s_waitcnt vmcnt(8)
	s_waitcnt lgkmcnt(0)
	s_barrier
	s_waitcnt lgkmcnt(7)
	v_mfma_f32_16x16x32_bf16 v[164:167], v[128:131], v[184:187], v[164:167]
	v_mfma_f32_16x16x32_bf16 v[160:163], v[152:155], v[184:187], v[160:163]
	s_waitcnt lgkmcnt(5)
	v_mfma_f32_16x16x32_bf16 v[136:139], v[128:131], v[192:195], v[136:139]
	v_mfma_f32_16x16x32_bf16 v[132:135], v[152:155], v[192:195], v[132:135]
	s_waitcnt lgkmcnt(3)
	v_mfma_f32_16x16x32_bf16 v[116:119], v[128:131], v[200:203], v[116:119]
	v_mfma_f32_16x16x32_bf16 v[112:115], v[152:155], v[200:203], v[112:115]
	s_waitcnt lgkmcnt(1)
	v_mfma_f32_16x16x32_bf16 v[76:79], v[128:131], v[224:227], v[76:79]
	v_mfma_f32_16x16x32_bf16 v[72:75], v[152:155], v[224:227], v[72:75]
	v_mfma_f32_16x16x32_bf16 v[164:167], v[140:143], v[188:191], v[164:167]
	v_mfma_f32_16x16x32_bf16 v[160:163], v[156:159], v[188:191], v[160:163]
	v_mfma_f32_16x16x32_bf16 v[136:139], v[140:143], v[196:199], v[136:139]
	v_mfma_f32_16x16x32_bf16 v[132:135], v[156:159], v[196:199], v[132:135]
	v_mfma_f32_16x16x32_bf16 v[116:119], v[140:143], v[204:207], v[116:119]
	v_mfma_f32_16x16x32_bf16 v[112:115], v[156:159], v[204:207], v[112:115]
	s_waitcnt lgkmcnt(0)
	v_mfma_f32_16x16x32_bf16 v[76:79], v[140:143], v[228:231], v[76:79]
	v_mfma_f32_16x16x32_bf16 v[72:75], v[156:159], v[228:231], v[72:75]
	v_mfma_f32_16x16x32_bf16 v[148:151], v[168:171], v[184:187], v[148:151]
	v_mfma_f32_16x16x32_bf16 v[144:147], v[176:179], v[184:187], v[144:147]
	v_mfma_f32_16x16x32_bf16 v[124:127], v[168:171], v[192:195], v[124:127]
	v_mfma_f32_16x16x32_bf16 v[120:123], v[176:179], v[192:195], v[120:123]
	v_mfma_f32_16x16x32_bf16 v[108:111], v[168:171], v[200:203], v[108:111]
	v_mfma_f32_16x16x32_bf16 v[104:107], v[176:179], v[200:203], v[104:107]
	v_mfma_f32_16x16x32_bf16 v[68:71], v[168:171], v[224:227], v[68:71]
	v_mfma_f32_16x16x32_bf16 v[64:67], v[176:179], v[224:227], v[64:67]
	v_mfma_f32_16x16x32_bf16 v[148:151], v[172:175], v[188:191], v[148:151]
	v_mfma_f32_16x16x32_bf16 v[144:147], v[180:183], v[188:191], v[144:147]
	v_mfma_f32_16x16x32_bf16 v[124:127], v[172:175], v[196:199], v[124:127]
	v_mfma_f32_16x16x32_bf16 v[120:123], v[180:183], v[196:199], v[120:123]
	v_mfma_f32_16x16x32_bf16 v[108:111], v[172:175], v[204:207], v[108:111]
	v_mfma_f32_16x16x32_bf16 v[104:107], v[180:183], v[204:207], v[104:107]
	v_mfma_f32_16x16x32_bf16 v[68:71], v[172:175], v[228:231], v[68:71]
	v_mfma_f32_16x16x32_bf16 v[64:67], v[180:183], v[228:231], v[64:67]
	s_barrier
	ds_read_b128 v[184:187], v223 offset:49152
	ds_read_b128 v[188:191], v223 offset:50176
	ds_read_b128 v[192:195], v223 offset:51200
	ds_read_b128 v[196:199], v223 offset:52224
	ds_read_b128 v[200:203], v223 offset:53248
	ds_read_b128 v[204:207], v223 offset:54272
	ds_read_b128 v[224:227], v223 offset:55296
	ds_read_b128 v[228:231], v223 offset:56320
	s_or_b32 s13, s12, 0x4000
	s_mov_b32 m0, s34
	s_nop 0
	buffer_load_dwordx4 v220, s[52:55], s13 offen lds
	s_add_i32 s12, s12, 0x164000
	s_mov_b32 m0, s82
	s_nop 0
	buffer_load_dwordx4 v221, s[52:55], s13 offen lds
	s_nop 7
	s_mov_b32 m0, s85
	s_nop 0
	buffer_load_dwordx4 v220, s[52:55], s12 offen lds
	s_nop 7
	s_mov_b32 m0, s86
	s_nop 0
	buffer_load_dwordx4 v221, s[52:55], s12 offen lds
	s_nop 7
	s_mov_b32 m0, s83
	s_nop 0
	buffer_load_dwordx4 v220, s[20:23], s11 offen lds
	s_nop 7
	s_mov_b32 m0, s84
	s_nop 0
	buffer_load_dwordx4 v221, s[20:23], s11 offen lds
	s_waitcnt vmcnt(8)
	s_waitcnt lgkmcnt(0)
	s_barrier
	s_waitcnt lgkmcnt(7)
	v_mfma_f32_16x16x32_bf16 v[60:63], v[128:131], v[184:187], v[60:63]
	v_mfma_f32_16x16x32_bf16 v[56:59], v[152:155], v[184:187], v[56:59]
	s_waitcnt lgkmcnt(5)
	v_mfma_f32_16x16x32_bf16 v[44:47], v[128:131], v[192:195], v[44:47]
	v_mfma_f32_16x16x32_bf16 v[40:43], v[152:155], v[192:195], v[40:43]
	s_waitcnt lgkmcnt(3)
	v_mfma_f32_16x16x32_bf16 v[28:31], v[128:131], v[200:203], v[28:31]
	v_mfma_f32_16x16x32_bf16 v[24:27], v[152:155], v[200:203], v[24:27]
	s_waitcnt lgkmcnt(1)
	v_mfma_f32_16x16x32_bf16 v[12:15], v[128:131], v[224:227], v[12:15]
	v_mfma_f32_16x16x32_bf16 v[8:11], v[152:155], v[224:227], v[8:11]
	v_mfma_f32_16x16x32_bf16 v[60:63], v[140:143], v[188:191], v[60:63]
	v_mfma_f32_16x16x32_bf16 v[56:59], v[156:159], v[188:191], v[56:59]
	v_mfma_f32_16x16x32_bf16 v[44:47], v[140:143], v[196:199], v[44:47]
	v_mfma_f32_16x16x32_bf16 v[40:43], v[156:159], v[196:199], v[40:43]
	v_mfma_f32_16x16x32_bf16 v[28:31], v[140:143], v[204:207], v[28:31]
	v_mfma_f32_16x16x32_bf16 v[24:27], v[156:159], v[204:207], v[24:27]
	s_waitcnt lgkmcnt(0)
	v_mfma_f32_16x16x32_bf16 v[12:15], v[140:143], v[228:231], v[12:15]
	v_mfma_f32_16x16x32_bf16 v[8:11], v[156:159], v[228:231], v[8:11]
	v_mfma_f32_16x16x32_bf16 v[52:55], v[168:171], v[184:187], v[52:55]
	v_mfma_f32_16x16x32_bf16 v[48:51], v[176:179], v[184:187], v[48:51]
	v_mfma_f32_16x16x32_bf16 v[36:39], v[168:171], v[192:195], v[36:39]
	v_mfma_f32_16x16x32_bf16 v[32:35], v[176:179], v[192:195], v[32:35]
	v_mfma_f32_16x16x32_bf16 v[20:23], v[168:171], v[200:203], v[20:23]
	v_mfma_f32_16x16x32_bf16 v[16:19], v[176:179], v[200:203], v[16:19]
	v_mfma_f32_16x16x32_bf16 v[4:7], v[168:171], v[224:227], v[4:7]
	v_mfma_f32_16x16x32_bf16 v[0:3], v[176:179], v[224:227], v[0:3]
	v_mfma_f32_16x16x32_bf16 v[52:55], v[172:175], v[188:191], v[52:55]
	v_mfma_f32_16x16x32_bf16 v[48:51], v[180:183], v[188:191], v[48:51]
	v_mfma_f32_16x16x32_bf16 v[36:39], v[172:175], v[196:199], v[36:39]
	v_mfma_f32_16x16x32_bf16 v[32:35], v[180:183], v[196:199], v[32:35]
	v_mfma_f32_16x16x32_bf16 v[20:23], v[172:175], v[204:207], v[20:23]
	v_mfma_f32_16x16x32_bf16 v[16:19], v[180:183], v[204:207], v[16:19]
	v_mfma_f32_16x16x32_bf16 v[4:7], v[172:175], v[228:231], v[4:7]
	v_mfma_f32_16x16x32_bf16 v[0:3], v[180:183], v[228:231], v[0:3]
	s_barrier
	s_add_i32 s10, s10, 2
	s_add_i32 s8, s8, 0x8000
	s_add_i32 s9, s9, 0x8000
.LBB0_885:
	v_add_u32_e32 v156, 0x10000, v222
	v_add_u32_e32 v180, 0x14000, v222
	ds_read_b128 v[128:131], v156
	ds_read_b128 v[140:143], v156 offset:1024
	ds_read_b128 v[152:155], v156 offset:2048
	ds_read_b128 v[156:159], v156 offset:3072
	ds_read_b128 v[168:171], v180
	ds_read_b128 v[172:175], v180 offset:1024
	ds_read_b128 v[176:179], v180 offset:2048
	ds_read_b128 v[180:183], v180 offset:3072
	s_add_i32 s11, s8, 0xffea4000
	s_cmpk_eq_i32 s10, 0x54
	s_cselect_b32 s13, s6, s11
	s_cselect_b32 s12, s7, s9
	s_or_b32 s11, s13, 0x4000
	ds_read_b128 v[184:187], v223
	ds_read_b128 v[188:191], v223 offset:1024
	ds_read_b128 v[192:195], v223 offset:2048
	ds_read_b128 v[196:199], v223 offset:3072
	ds_read_b128 v[200:203], v223 offset:4096
	ds_read_b128 v[204:207], v223 offset:5120
	ds_read_b128 v[224:227], v223 offset:6144
	ds_read_b128 v[228:231], v223 offset:7168
	s_mov_b32 m0, s87
	s_nop 0
	buffer_load_dwordx4 v220, s[20:23], s8 offen lds
	s_nop 7
	s_mov_b32 m0, s89
	s_nop 0
	buffer_load_dwordx4 v221, s[20:23], s8 offen lds
	s_waitcnt vmcnt(8)
	s_waitcnt lgkmcnt(0)
	s_barrier
	s_waitcnt lgkmcnt(7)
	v_mfma_f32_16x16x32_bf16 v[164:167], v[128:131], v[184:187], v[164:167]
	v_mfma_f32_16x16x32_bf16 v[160:163], v[152:155], v[184:187], v[160:163]
	s_waitcnt lgkmcnt(5)
	v_mfma_f32_16x16x32_bf16 v[136:139], v[128:131], v[192:195], v[136:139]
	v_mfma_f32_16x16x32_bf16 v[132:135], v[152:155], v[192:195], v[132:135]
	s_waitcnt lgkmcnt(3)
	v_mfma_f32_16x16x32_bf16 v[116:119], v[128:131], v[200:203], v[116:119]
	v_mfma_f32_16x16x32_bf16 v[112:115], v[152:155], v[200:203], v[112:115]
	s_waitcnt lgkmcnt(1)
	v_mfma_f32_16x16x32_bf16 v[76:79], v[128:131], v[224:227], v[76:79]
	v_mfma_f32_16x16x32_bf16 v[72:75], v[152:155], v[224:227], v[72:75]
	v_mfma_f32_16x16x32_bf16 v[164:167], v[140:143], v[188:191], v[164:167]
	v_mfma_f32_16x16x32_bf16 v[160:163], v[156:159], v[188:191], v[160:163]
	v_mfma_f32_16x16x32_bf16 v[136:139], v[140:143], v[196:199], v[136:139]
	v_mfma_f32_16x16x32_bf16 v[132:135], v[156:159], v[196:199], v[132:135]
	v_mfma_f32_16x16x32_bf16 v[116:119], v[140:143], v[204:207], v[116:119]
	v_mfma_f32_16x16x32_bf16 v[112:115], v[156:159], v[204:207], v[112:115]
	s_waitcnt lgkmcnt(0)
	v_mfma_f32_16x16x32_bf16 v[76:79], v[140:143], v[228:231], v[76:79]
	v_mfma_f32_16x16x32_bf16 v[72:75], v[156:159], v[228:231], v[72:75]
	v_mfma_f32_16x16x32_bf16 v[148:151], v[168:171], v[184:187], v[148:151]
	v_mfma_f32_16x16x32_bf16 v[144:147], v[176:179], v[184:187], v[144:147]
	v_mfma_f32_16x16x32_bf16 v[124:127], v[168:171], v[192:195], v[124:127]
	v_mfma_f32_16x16x32_bf16 v[120:123], v[176:179], v[192:195], v[120:123]
	v_mfma_f32_16x16x32_bf16 v[108:111], v[168:171], v[200:203], v[108:111]
	v_mfma_f32_16x16x32_bf16 v[104:107], v[176:179], v[200:203], v[104:107]
	v_mfma_f32_16x16x32_bf16 v[68:71], v[168:171], v[224:227], v[68:71]
	v_mfma_f32_16x16x32_bf16 v[64:67], v[176:179], v[224:227], v[64:67]
	v_mfma_f32_16x16x32_bf16 v[148:151], v[172:175], v[188:191], v[148:151]
	v_mfma_f32_16x16x32_bf16 v[144:147], v[180:183], v[188:191], v[144:147]
	v_mfma_f32_16x16x32_bf16 v[124:127], v[172:175], v[196:199], v[124:127]
	v_mfma_f32_16x16x32_bf16 v[120:123], v[180:183], v[196:199], v[120:123]
	v_mfma_f32_16x16x32_bf16 v[108:111], v[172:175], v[204:207], v[108:111]
	v_mfma_f32_16x16x32_bf16 v[104:107], v[180:183], v[204:207], v[104:107]
	v_mfma_f32_16x16x32_bf16 v[68:71], v[172:175], v[228:231], v[68:71]
	v_mfma_f32_16x16x32_bf16 v[64:67], v[180:183], v[228:231], v[64:67]
	s_barrier
	ds_read_b128 v[184:187], v223 offset:16384
	ds_read_b128 v[188:191], v223 offset:17408
	ds_read_b128 v[192:195], v223 offset:18432
	ds_read_b128 v[196:199], v223 offset:19456
	ds_read_b128 v[200:203], v223 offset:20480
	ds_read_b128 v[204:207], v223 offset:21504
	ds_read_b128 v[224:227], v223 offset:22528
	ds_read_b128 v[228:231], v223 offset:23552
	s_mov_b32 m0, s51
	s_nop 0
	buffer_load_dwordx4 v220, s[52:55], s12 offen lds
	s_add_i32 s14, s12, 0x160000
	s_mov_b32 m0, s74
	s_nop 0
	buffer_load_dwordx4 v221, s[52:55], s12 offen lds
	s_nop 7
	s_mov_b32 m0, s75
	s_nop 0
	buffer_load_dwordx4 v220, s[52:55], s14 offen lds
	s_nop 7
	s_mov_b32 m0, s76
	s_nop 0
	buffer_load_dwordx4 v221, s[52:55], s14 offen lds
	s_nop 7
	s_mov_b32 m0, s31
	s_nop 0
	buffer_load_dwordx4 v220, s[20:23], s13 offen lds
	s_nop 7
	s_mov_b32 m0, s77
	s_nop 0
	buffer_load_dwordx4 v221, s[20:23], s13 offen lds
	s_waitcnt vmcnt(8)
	s_waitcnt lgkmcnt(0)
	s_barrier
	s_waitcnt lgkmcnt(7)
	v_mfma_f32_16x16x32_bf16 v[60:63], v[128:131], v[184:187], v[60:63]
	v_mfma_f32_16x16x32_bf16 v[56:59], v[152:155], v[184:187], v[56:59]
	s_waitcnt lgkmcnt(5)
	v_mfma_f32_16x16x32_bf16 v[44:47], v[128:131], v[192:195], v[44:47]
	v_mfma_f32_16x16x32_bf16 v[40:43], v[152:155], v[192:195], v[40:43]
	s_waitcnt lgkmcnt(3)
	v_mfma_f32_16x16x32_bf16 v[28:31], v[128:131], v[200:203], v[28:31]
	v_mfma_f32_16x16x32_bf16 v[24:27], v[152:155], v[200:203], v[24:27]
	s_waitcnt lgkmcnt(1)
	v_mfma_f32_16x16x32_bf16 v[12:15], v[128:131], v[224:227], v[12:15]
	v_mfma_f32_16x16x32_bf16 v[8:11], v[152:155], v[224:227], v[8:11]
	v_mfma_f32_16x16x32_bf16 v[60:63], v[140:143], v[188:191], v[60:63]
	v_mfma_f32_16x16x32_bf16 v[56:59], v[156:159], v[188:191], v[56:59]
	v_mfma_f32_16x16x32_bf16 v[44:47], v[140:143], v[196:199], v[44:47]
	v_mfma_f32_16x16x32_bf16 v[40:43], v[156:159], v[196:199], v[40:43]
	v_mfma_f32_16x16x32_bf16 v[28:31], v[140:143], v[204:207], v[28:31]
	v_mfma_f32_16x16x32_bf16 v[24:27], v[156:159], v[204:207], v[24:27]
	s_waitcnt lgkmcnt(0)
	v_mfma_f32_16x16x32_bf16 v[12:15], v[140:143], v[228:231], v[12:15]
	v_mfma_f32_16x16x32_bf16 v[8:11], v[156:159], v[228:231], v[8:11]
	v_mfma_f32_16x16x32_bf16 v[52:55], v[168:171], v[184:187], v[52:55]
	v_mfma_f32_16x16x32_bf16 v[48:51], v[176:179], v[184:187], v[48:51]
	v_mfma_f32_16x16x32_bf16 v[36:39], v[168:171], v[192:195], v[36:39]
	v_mfma_f32_16x16x32_bf16 v[32:35], v[176:179], v[192:195], v[32:35]
	v_mfma_f32_16x16x32_bf16 v[20:23], v[168:171], v[200:203], v[20:23]
	v_mfma_f32_16x16x32_bf16 v[16:19], v[176:179], v[200:203], v[16:19]
	v_mfma_f32_16x16x32_bf16 v[4:7], v[168:171], v[224:227], v[4:7]
	v_mfma_f32_16x16x32_bf16 v[0:3], v[176:179], v[224:227], v[0:3]
	v_mfma_f32_16x16x32_bf16 v[52:55], v[172:175], v[188:191], v[52:55]
	v_mfma_f32_16x16x32_bf16 v[48:51], v[180:183], v[188:191], v[48:51]
	v_mfma_f32_16x16x32_bf16 v[36:39], v[172:175], v[196:199], v[36:39]
	v_mfma_f32_16x16x32_bf16 v[32:35], v[180:183], v[196:199], v[32:35]
	v_mfma_f32_16x16x32_bf16 v[20:23], v[172:175], v[204:207], v[20:23]
	v_mfma_f32_16x16x32_bf16 v[16:19], v[180:183], v[204:207], v[16:19]
	v_mfma_f32_16x16x32_bf16 v[4:7], v[172:175], v[228:231], v[4:7]
	v_mfma_f32_16x16x32_bf16 v[0:3], v[180:183], v[228:231], v[0:3]
	s_barrier
	v_add_u32_e32 v156, 0x18000, v222
	v_add_u32_e32 v180, 0x1c000, v222
	ds_read_b128 v[128:131], v156
	ds_read_b128 v[140:143], v156 offset:1024
	ds_read_b128 v[152:155], v156 offset:2048
	ds_read_b128 v[156:159], v156 offset:3072
	ds_read_b128 v[168:171], v180
	ds_read_b128 v[172:175], v180 offset:1024
	ds_read_b128 v[176:179], v180 offset:2048
	ds_read_b128 v[180:183], v180 offset:3072
	ds_read_b128 v[184:187], v223 offset:32768
	ds_read_b128 v[188:191], v223 offset:33792
	ds_read_b128 v[192:195], v223 offset:34816
	ds_read_b128 v[196:199], v223 offset:35840
	ds_read_b128 v[200:203], v223 offset:36864
	ds_read_b128 v[204:207], v223 offset:37888
	ds_read_b128 v[224:227], v223 offset:38912
	ds_read_b128 v[228:231], v223 offset:39936
	s_add_i32 s13, s13, 0x160000
	s_mov_b32 m0, s78
	s_nop 0
	buffer_load_dwordx4 v220, s[20:23], s13 offen lds
	s_nop 7
	s_mov_b32 m0, s79
	s_nop 0
	buffer_load_dwordx4 v221, s[20:23], s13 offen lds
	s_waitcnt vmcnt(8)
	s_waitcnt lgkmcnt(0)
	s_barrier
	s_waitcnt lgkmcnt(7)
	v_mfma_f32_16x16x32_bf16 v[164:167], v[128:131], v[184:187], v[164:167]
	v_mfma_f32_16x16x32_bf16 v[160:163], v[152:155], v[184:187], v[160:163]
	s_waitcnt lgkmcnt(5)
	v_mfma_f32_16x16x32_bf16 v[136:139], v[128:131], v[192:195], v[136:139]
	v_mfma_f32_16x16x32_bf16 v[132:135], v[152:155], v[192:195], v[132:135]
	s_waitcnt lgkmcnt(3)
	v_mfma_f32_16x16x32_bf16 v[116:119], v[128:131], v[200:203], v[116:119]
	v_mfma_f32_16x16x32_bf16 v[112:115], v[152:155], v[200:203], v[112:115]
	s_waitcnt lgkmcnt(1)
	v_mfma_f32_16x16x32_bf16 v[76:79], v[128:131], v[224:227], v[76:79]
	v_mfma_f32_16x16x32_bf16 v[72:75], v[152:155], v[224:227], v[72:75]
	v_mfma_f32_16x16x32_bf16 v[164:167], v[140:143], v[188:191], v[164:167]
	v_mfma_f32_16x16x32_bf16 v[160:163], v[156:159], v[188:191], v[160:163]
	v_mfma_f32_16x16x32_bf16 v[136:139], v[140:143], v[196:199], v[136:139]
	v_mfma_f32_16x16x32_bf16 v[132:135], v[156:159], v[196:199], v[132:135]
	v_mfma_f32_16x16x32_bf16 v[116:119], v[140:143], v[204:207], v[116:119]
	v_mfma_f32_16x16x32_bf16 v[112:115], v[156:159], v[204:207], v[112:115]
	s_waitcnt lgkmcnt(0)
	v_mfma_f32_16x16x32_bf16 v[76:79], v[140:143], v[228:231], v[76:79]
	v_mfma_f32_16x16x32_bf16 v[72:75], v[156:159], v[228:231], v[72:75]
	v_mfma_f32_16x16x32_bf16 v[148:151], v[168:171], v[184:187], v[148:151]
	v_mfma_f32_16x16x32_bf16 v[144:147], v[176:179], v[184:187], v[144:147]
	v_mfma_f32_16x16x32_bf16 v[124:127], v[168:171], v[192:195], v[124:127]
	v_mfma_f32_16x16x32_bf16 v[120:123], v[176:179], v[192:195], v[120:123]
	v_mfma_f32_16x16x32_bf16 v[108:111], v[168:171], v[200:203], v[108:111]
	v_mfma_f32_16x16x32_bf16 v[104:107], v[176:179], v[200:203], v[104:107]
	v_mfma_f32_16x16x32_bf16 v[68:71], v[168:171], v[224:227], v[68:71]
	v_mfma_f32_16x16x32_bf16 v[64:67], v[176:179], v[224:227], v[64:67]
	v_mfma_f32_16x16x32_bf16 v[148:151], v[172:175], v[188:191], v[148:151]
	v_mfma_f32_16x16x32_bf16 v[144:147], v[180:183], v[188:191], v[144:147]
	v_mfma_f32_16x16x32_bf16 v[124:127], v[172:175], v[196:199], v[124:127]
	v_mfma_f32_16x16x32_bf16 v[120:123], v[180:183], v[196:199], v[120:123]
	v_mfma_f32_16x16x32_bf16 v[108:111], v[172:175], v[204:207], v[108:111]
	v_mfma_f32_16x16x32_bf16 v[104:107], v[180:183], v[204:207], v[104:107]
	v_mfma_f32_16x16x32_bf16 v[68:71], v[172:175], v[228:231], v[68:71]
	v_mfma_f32_16x16x32_bf16 v[64:67], v[180:183], v[228:231], v[64:67]
	s_barrier
	ds_read_b128 v[184:187], v223 offset:49152
	ds_read_b128 v[188:191], v223 offset:50176
	ds_read_b128 v[192:195], v223 offset:51200
	ds_read_b128 v[196:199], v223 offset:52224
	ds_read_b128 v[200:203], v223 offset:53248
	ds_read_b128 v[204:207], v223 offset:54272
	ds_read_b128 v[224:227], v223 offset:55296
	ds_read_b128 v[228:231], v223 offset:56320
	s_or_b32 s13, s12, 0x4000
	s_mov_b32 m0, s34
	s_nop 0
	buffer_load_dwordx4 v220, s[52:55], s13 offen lds
	s_add_i32 s12, s12, 0x164000
	s_mov_b32 m0, s82
	s_nop 0
	buffer_load_dwordx4 v221, s[52:55], s13 offen lds
	s_nop 7
	s_mov_b32 m0, s85
	s_nop 0
	buffer_load_dwordx4 v220, s[52:55], s12 offen lds
	s_nop 7
	s_mov_b32 m0, s86
	s_nop 0
	buffer_load_dwordx4 v221, s[52:55], s12 offen lds
	s_nop 7
	s_mov_b32 m0, s83
	s_nop 0
	buffer_load_dwordx4 v220, s[20:23], s11 offen lds
	s_nop 7
	s_mov_b32 m0, s84
	s_nop 0
	buffer_load_dwordx4 v221, s[20:23], s11 offen lds
	s_waitcnt vmcnt(8)
	s_waitcnt lgkmcnt(0)
	s_barrier
	s_waitcnt lgkmcnt(7)
	v_mfma_f32_16x16x32_bf16 v[60:63], v[128:131], v[184:187], v[60:63]
	v_mfma_f32_16x16x32_bf16 v[56:59], v[152:155], v[184:187], v[56:59]
	s_waitcnt lgkmcnt(5)
	v_mfma_f32_16x16x32_bf16 v[44:47], v[128:131], v[192:195], v[44:47]
	v_mfma_f32_16x16x32_bf16 v[40:43], v[152:155], v[192:195], v[40:43]
	s_waitcnt lgkmcnt(3)
	v_mfma_f32_16x16x32_bf16 v[28:31], v[128:131], v[200:203], v[28:31]
	v_mfma_f32_16x16x32_bf16 v[24:27], v[152:155], v[200:203], v[24:27]
	s_waitcnt lgkmcnt(1)
	v_mfma_f32_16x16x32_bf16 v[12:15], v[128:131], v[224:227], v[12:15]
	v_mfma_f32_16x16x32_bf16 v[8:11], v[152:155], v[224:227], v[8:11]
	v_mfma_f32_16x16x32_bf16 v[60:63], v[140:143], v[188:191], v[60:63]
	v_mfma_f32_16x16x32_bf16 v[56:59], v[156:159], v[188:191], v[56:59]
	v_mfma_f32_16x16x32_bf16 v[44:47], v[140:143], v[196:199], v[44:47]
	v_mfma_f32_16x16x32_bf16 v[40:43], v[156:159], v[196:199], v[40:43]
	v_mfma_f32_16x16x32_bf16 v[28:31], v[140:143], v[204:207], v[28:31]
	v_mfma_f32_16x16x32_bf16 v[24:27], v[156:159], v[204:207], v[24:27]
	s_waitcnt lgkmcnt(0)
	v_mfma_f32_16x16x32_bf16 v[12:15], v[140:143], v[228:231], v[12:15]
	v_mfma_f32_16x16x32_bf16 v[8:11], v[156:159], v[228:231], v[8:11]
	v_mfma_f32_16x16x32_bf16 v[52:55], v[168:171], v[184:187], v[52:55]
	v_mfma_f32_16x16x32_bf16 v[48:51], v[176:179], v[184:187], v[48:51]
	v_mfma_f32_16x16x32_bf16 v[36:39], v[168:171], v[192:195], v[36:39]
	v_mfma_f32_16x16x32_bf16 v[32:35], v[176:179], v[192:195], v[32:35]
	v_mfma_f32_16x16x32_bf16 v[20:23], v[168:171], v[200:203], v[20:23]
	v_mfma_f32_16x16x32_bf16 v[16:19], v[176:179], v[200:203], v[16:19]
	v_mfma_f32_16x16x32_bf16 v[4:7], v[168:171], v[224:227], v[4:7]
	v_mfma_f32_16x16x32_bf16 v[0:3], v[176:179], v[224:227], v[0:3]
	v_mfma_f32_16x16x32_bf16 v[52:55], v[172:175], v[188:191], v[52:55]
	v_mfma_f32_16x16x32_bf16 v[48:51], v[180:183], v[188:191], v[48:51]
	v_mfma_f32_16x16x32_bf16 v[36:39], v[172:175], v[196:199], v[36:39]
	v_mfma_f32_16x16x32_bf16 v[32:35], v[180:183], v[196:199], v[32:35]
	v_mfma_f32_16x16x32_bf16 v[20:23], v[172:175], v[204:207], v[20:23]
	v_mfma_f32_16x16x32_bf16 v[16:19], v[180:183], v[204:207], v[16:19]
	v_mfma_f32_16x16x32_bf16 v[4:7], v[172:175], v[228:231], v[4:7]
	v_mfma_f32_16x16x32_bf16 v[0:3], v[180:183], v[228:231], v[0:3]
	s_barrier
	s_add_i32 s10, s10, 2
	s_add_i32 s8, s8, 0x8000
	s_add_i32 s9, s9, 0x8000
	s_cmpk_gt_u32 s10, 0x55
	s_cbranch_scc0 .LBB0_885
